# c2 plus LDS-DMA address generation moved from per-lane 64-bit VALU adds to scalar-base addressing (41 sites in the 8 K-loops)
# baseline (speedup 1.0000x reference)
.LBB0_112:
	s_add_u32 s16, vcc_lo, 0xfff80080
	s_addc_u32 s17, vcc_hi, -1
	s_add_i32 s24, 0, 0x10000
	s_cmp_eq_u32 s96, 28
	s_cselect_b32 s23, s65, s17
	s_cselect_b32 s22, s75, s16
	v_add_u32_e32 v0, s24, v173
	s_cselect_b32 s17, s51, s63
	s_cselect_b32 s16, s89, s62
	s_add_i32 s97, 0, 0x14000
	ds_read_b128 v[130:133], v0
	ds_read_b128 v[134:137], v0 offset:1024
	ds_read_b128 v[138:141], v0 offset:2048
	ds_read_b128 v[142:145], v0 offset:3072
	v_add_u32_e32 v0, s97, v173
	s_waitcnt lgkmcnt(0)
	ds_read_b128 v[158:161], v0
	ds_read_b128 v[162:165], v0 offset:1024
	ds_read_b128 v[166:169], v0 offset:2048
	ds_read_b128 v[182:185], v0 offset:3072
	s_add_i32 m0, s56, 0xc000
	ds_read_b128 v[186:189], v181
	ds_read_b128 v[190:193], v181 offset:1024
	ds_read_b128 v[194:197], v181 offset:2048
	ds_read_b128 v[198:201], v181 offset:3072
	ds_read_b128 v[202:205], v181 offset:4096
	ds_read_b128 v[206:209], v181 offset:5120
	ds_read_b128 v[210:213], v181 offset:6144
	ds_read_b128 v[214:217], v181 offset:7168
	global_load_lds_dwordx4 v154, vcc
	s_add_i32 m0, s56, 0xe000
	s_nop 0
	global_load_lds_dwordx4 v156, vcc
	s_cmp_lg_u32 s100, 0
	s_cbranch_scc1 .Lcw_g1_p1
	s_waitcnt vmcnt(8)
.Lcw_g1_c1:
	s_waitcnt lgkmcnt(0)
	s_setprio 1
	s_barrier
	v_mfma_f32_16x16x32_bf16 v[126:129], v[130:133], v[186:189], v[126:129]
	v_mfma_f32_16x16x32_bf16 v[122:125], v[138:141], v[186:189], v[122:125]
	v_mfma_f32_16x16x32_bf16 v[110:113], v[130:133], v[194:197], v[110:113]
	v_mfma_f32_16x16x32_bf16 v[106:109], v[138:141], v[194:197], v[106:109]
	v_mfma_f32_16x16x32_bf16 v[94:97], v[130:133], v[202:205], v[94:97]
	v_mfma_f32_16x16x32_bf16 v[90:93], v[138:141], v[202:205], v[90:93]
	v_mfma_f32_16x16x32_bf16 v[78:81], v[130:133], v[210:213], v[78:81]
	v_mfma_f32_16x16x32_bf16 v[74:77], v[138:141], v[210:213], v[74:77]
	v_mfma_f32_16x16x32_bf16 v[126:129], v[134:137], v[190:193], v[126:129]
	v_mfma_f32_16x16x32_bf16 v[122:125], v[142:145], v[190:193], v[122:125]
	v_mfma_f32_16x16x32_bf16 v[110:113], v[134:137], v[198:201], v[110:113]
	v_mfma_f32_16x16x32_bf16 v[106:109], v[142:145], v[198:201], v[106:109]
	v_mfma_f32_16x16x32_bf16 v[94:97], v[134:137], v[206:209], v[94:97]
	v_mfma_f32_16x16x32_bf16 v[90:93], v[142:145], v[206:209], v[90:93]
	v_mfma_f32_16x16x32_bf16 v[78:81], v[134:137], v[214:217], v[78:81]
	v_mfma_f32_16x16x32_bf16 v[74:77], v[142:145], v[214:217], v[74:77]
	s_setprio 0
	s_setprio 1
	v_mfma_f32_16x16x32_bf16 v[118:121], v[158:161], v[186:189], v[118:121]
	v_mfma_f32_16x16x32_bf16 v[114:117], v[166:169], v[186:189], v[114:117]
	v_mfma_f32_16x16x32_bf16 v[102:105], v[158:161], v[194:197], v[102:105]
	v_mfma_f32_16x16x32_bf16 v[98:101], v[166:169], v[194:197], v[98:101]
	v_mfma_f32_16x16x32_bf16 v[86:89], v[158:161], v[202:205], v[86:89]
	v_mfma_f32_16x16x32_bf16 v[82:85], v[166:169], v[202:205], v[82:85]
	v_mfma_f32_16x16x32_bf16 v[70:73], v[158:161], v[210:213], v[70:73]
	v_mfma_f32_16x16x32_bf16 v[66:69], v[166:169], v[210:213], v[66:69]
	v_mfma_f32_16x16x32_bf16 v[118:121], v[162:165], v[190:193], v[118:121]
	v_mfma_f32_16x16x32_bf16 v[114:117], v[182:185], v[190:193], v[114:117]
	v_mfma_f32_16x16x32_bf16 v[102:105], v[162:165], v[198:201], v[102:105]
	v_mfma_f32_16x16x32_bf16 v[98:101], v[182:185], v[198:201], v[98:101]
	v_mfma_f32_16x16x32_bf16 v[86:89], v[162:165], v[206:209], v[86:89]
	v_mfma_f32_16x16x32_bf16 v[82:85], v[182:185], v[206:209], v[82:85]
	v_mfma_f32_16x16x32_bf16 v[70:73], v[162:165], v[214:217], v[70:73]
	v_mfma_f32_16x16x32_bf16 v[66:69], v[182:185], v[214:217], v[66:69]
	s_barrier
	s_setprio 0
	s_add_i32 s24, s24, s77
	v_lshl_add_u64 v[170:171], s[16:17], 0, v[150:151]
	s_mov_b32 m0, s24
	ds_read_b128 v[186:189], v181 offset:16384
	ds_read_b128 v[190:193], v181 offset:17408
	ds_read_b128 v[194:197], v181 offset:18432
	ds_read_b128 v[198:201], v181 offset:19456
	ds_read_b128 v[202:205], v181 offset:20480
	ds_read_b128 v[206:209], v181 offset:21504
	ds_read_b128 v[210:213], v181 offset:22528
	ds_read_b128 v[214:217], v181 offset:23552
	global_load_lds_dwordx4 v[170:171], off
	s_add_i32 m0, s24, 0x2000
	s_add_u32 s66, s16, 0x80000
	v_lshl_add_u64 v[218:219], s[16:17], 0, v[146:147]
	s_addc_u32 s67, s17, 0
	s_add_i32 s24, s97, s77
	global_load_lds_dwordx4 v[218:219], off
	s_mov_b32 m0, s24
	v_lshl_add_u64 v[222:223], s[22:23], 0, v[148:149]
	global_load_lds_dwordx4 v150, s[66:67]
	s_add_i32 m0, s24, 0x2000
	s_nop 0
	global_load_lds_dwordx4 v146, s[66:67]
	v_lshl_add_u64 v[220:221], s[22:23], 0, v[152:153]
	s_mov_b32 m0, s56
	s_nop 0
	global_load_lds_dwordx4 v[220:221], off
	s_mov_b32 m0, s57
	s_nop 0
	global_load_lds_dwordx4 v[222:223], off
	s_cmp_lg_u32 s100, 0
	s_cbranch_scc1 .Lcw_g1_p2
	s_waitcnt vmcnt(8)
.Lcw_g1_c2:
	s_waitcnt lgkmcnt(0)
	s_setprio 1
	s_barrier
	v_mfma_f32_16x16x32_bf16 v[62:65], v[130:133], v[186:189], v[62:65]
	v_mfma_f32_16x16x32_bf16 v[58:61], v[138:141], v[186:189], v[58:61]
	v_mfma_f32_16x16x32_bf16 v[46:49], v[130:133], v[194:197], v[46:49]
	v_mfma_f32_16x16x32_bf16 v[42:45], v[138:141], v[194:197], v[42:45]
	v_mfma_f32_16x16x32_bf16 v[30:33], v[130:133], v[202:205], v[30:33]
	v_mfma_f32_16x16x32_bf16 v[26:29], v[138:141], v[202:205], v[26:29]
	v_mfma_f32_16x16x32_bf16 v[14:17], v[130:133], v[210:213], v[14:17]
	v_mfma_f32_16x16x32_bf16 v[10:13], v[138:141], v[210:213], v[10:13]
	v_mfma_f32_16x16x32_bf16 v[62:65], v[134:137], v[190:193], v[62:65]
	v_mfma_f32_16x16x32_bf16 v[58:61], v[142:145], v[190:193], v[58:61]
	v_mfma_f32_16x16x32_bf16 v[46:49], v[134:137], v[198:201], v[46:49]
	v_mfma_f32_16x16x32_bf16 v[42:45], v[142:145], v[198:201], v[42:45]
	v_mfma_f32_16x16x32_bf16 v[30:33], v[134:137], v[206:209], v[30:33]
	v_mfma_f32_16x16x32_bf16 v[26:29], v[142:145], v[206:209], v[26:29]
	v_mfma_f32_16x16x32_bf16 v[14:17], v[134:137], v[214:217], v[14:17]
	v_mfma_f32_16x16x32_bf16 v[10:13], v[142:145], v[214:217], v[10:13]
	s_setprio 0
	s_setprio 1
	v_mfma_f32_16x16x32_bf16 v[54:57], v[158:161], v[186:189], v[54:57]
	v_mfma_f32_16x16x32_bf16 v[50:53], v[166:169], v[186:189], v[50:53]
	v_mfma_f32_16x16x32_bf16 v[38:41], v[158:161], v[194:197], v[38:41]
	v_mfma_f32_16x16x32_bf16 v[34:37], v[166:169], v[194:197], v[34:37]
	v_mfma_f32_16x16x32_bf16 v[22:25], v[158:161], v[202:205], v[22:25]
	v_mfma_f32_16x16x32_bf16 v[18:21], v[166:169], v[202:205], v[18:21]
	v_mfma_f32_16x16x32_bf16 v[6:9], v[158:161], v[210:213], v[6:9]
	v_mfma_f32_16x16x32_bf16 v[2:5], v[166:169], v[210:213], v[2:5]
	v_mfma_f32_16x16x32_bf16 v[54:57], v[162:165], v[190:193], v[54:57]
	v_mfma_f32_16x16x32_bf16 v[50:53], v[182:185], v[190:193], v[50:53]
	v_mfma_f32_16x16x32_bf16 v[38:41], v[162:165], v[198:201], v[38:41]
	v_mfma_f32_16x16x32_bf16 v[34:37], v[182:185], v[198:201], v[34:37]
	v_mfma_f32_16x16x32_bf16 v[22:25], v[162:165], v[206:209], v[22:25]
	v_mfma_f32_16x16x32_bf16 v[18:21], v[182:185], v[206:209], v[18:21]
	v_mfma_f32_16x16x32_bf16 v[6:9], v[162:165], v[214:217], v[6:9]
	v_mfma_f32_16x16x32_bf16 v[2:5], v[182:185], v[214:217], v[2:5]
	s_barrier
	s_setprio 0
	s_add_i32 s24, 0, 0x18000
	v_add_u32_e32 v0, s24, v173
	s_add_i32 s66, 0, 0x1c000
	ds_read_b128 v[130:133], v0
	ds_read_b128 v[134:137], v0 offset:1024
	ds_read_b128 v[138:141], v0 offset:2048
	ds_read_b128 v[142:145], v0 offset:3072
	v_add_u32_e32 v0, s66, v173
	ds_read_b128 v[158:161], v0
	ds_read_b128 v[162:165], v0 offset:1024
	ds_read_b128 v[166:169], v0 offset:2048
	ds_read_b128 v[182:185], v0 offset:3072
	s_add_u32 s22, s22, 0x80000
	s_addc_u32 s23, s23, 0
	s_mov_b32 m0, s42
	ds_read_b128 v[186:189], v181 offset:32768
	ds_read_b128 v[190:193], v181 offset:33792
	ds_read_b128 v[194:197], v181 offset:34816
	ds_read_b128 v[198:201], v181 offset:35840
	ds_read_b128 v[202:205], v181 offset:36864
	ds_read_b128 v[206:209], v181 offset:37888
	ds_read_b128 v[210:213], v181 offset:38912
	ds_read_b128 v[214:217], v181 offset:39936
	global_load_lds_dwordx4 v152, s[22:23]
	s_mov_b32 m0, s43
	s_nop 0
	global_load_lds_dwordx4 v148, s[22:23]
	s_waitcnt vmcnt(8)
	s_waitcnt lgkmcnt(0)
	s_setprio 1
	s_barrier
	v_mfma_f32_16x16x32_bf16 v[126:129], v[130:133], v[186:189], v[126:129]
	v_mfma_f32_16x16x32_bf16 v[122:125], v[138:141], v[186:189], v[122:125]
	v_mfma_f32_16x16x32_bf16 v[110:113], v[130:133], v[194:197], v[110:113]
	v_mfma_f32_16x16x32_bf16 v[106:109], v[138:141], v[194:197], v[106:109]
	v_mfma_f32_16x16x32_bf16 v[94:97], v[130:133], v[202:205], v[94:97]
	v_mfma_f32_16x16x32_bf16 v[90:93], v[138:141], v[202:205], v[90:93]
	v_mfma_f32_16x16x32_bf16 v[78:81], v[130:133], v[210:213], v[78:81]
	v_mfma_f32_16x16x32_bf16 v[74:77], v[138:141], v[210:213], v[74:77]
	v_mfma_f32_16x16x32_bf16 v[126:129], v[134:137], v[190:193], v[126:129]
	v_mfma_f32_16x16x32_bf16 v[122:125], v[142:145], v[190:193], v[122:125]
	v_mfma_f32_16x16x32_bf16 v[110:113], v[134:137], v[198:201], v[110:113]
	v_mfma_f32_16x16x32_bf16 v[106:109], v[142:145], v[198:201], v[106:109]
	v_mfma_f32_16x16x32_bf16 v[94:97], v[134:137], v[206:209], v[94:97]
	v_mfma_f32_16x16x32_bf16 v[90:93], v[142:145], v[206:209], v[90:93]
	v_mfma_f32_16x16x32_bf16 v[78:81], v[134:137], v[214:217], v[78:81]
	v_mfma_f32_16x16x32_bf16 v[74:77], v[142:145], v[214:217], v[74:77]
	s_setprio 0
	s_setprio 1
	v_mfma_f32_16x16x32_bf16 v[118:121], v[158:161], v[186:189], v[118:121]
	v_mfma_f32_16x16x32_bf16 v[114:117], v[166:169], v[186:189], v[114:117]
	v_mfma_f32_16x16x32_bf16 v[102:105], v[158:161], v[194:197], v[102:105]
	v_mfma_f32_16x16x32_bf16 v[98:101], v[166:169], v[194:197], v[98:101]
	v_mfma_f32_16x16x32_bf16 v[86:89], v[158:161], v[202:205], v[86:89]
	v_mfma_f32_16x16x32_bf16 v[82:85], v[166:169], v[202:205], v[82:85]
	v_mfma_f32_16x16x32_bf16 v[70:73], v[158:161], v[210:213], v[70:73]
	v_mfma_f32_16x16x32_bf16 v[66:69], v[166:169], v[210:213], v[66:69]
	v_mfma_f32_16x16x32_bf16 v[118:121], v[162:165], v[190:193], v[118:121]
	v_mfma_f32_16x16x32_bf16 v[114:117], v[182:185], v[190:193], v[114:117]
	v_mfma_f32_16x16x32_bf16 v[102:105], v[162:165], v[198:201], v[102:105]
	v_mfma_f32_16x16x32_bf16 v[98:101], v[182:185], v[198:201], v[98:101]
	v_mfma_f32_16x16x32_bf16 v[86:89], v[162:165], v[206:209], v[86:89]
	v_mfma_f32_16x16x32_bf16 v[82:85], v[182:185], v[206:209], v[82:85]
	v_mfma_f32_16x16x32_bf16 v[70:73], v[162:165], v[214:217], v[70:73]
	v_mfma_f32_16x16x32_bf16 v[66:69], v[182:185], v[214:217], v[66:69]
	s_barrier
	s_setprio 0
	s_add_i32 s22, s24, s77
	v_lshl_add_u64 v[170:171], v[170:171], 0, s[34:35]
	s_mov_b32 m0, s22
	ds_read_b128 v[186:189], v181 offset:49152
	ds_read_b128 v[190:193], v181 offset:50176
	ds_read_b128 v[194:197], v181 offset:51200
	ds_read_b128 v[198:201], v181 offset:52224
	ds_read_b128 v[202:205], v181 offset:53248
	ds_read_b128 v[206:209], v181 offset:54272
	ds_read_b128 v[210:213], v181 offset:55296
	ds_read_b128 v[214:217], v181 offset:56320
	global_load_lds_dwordx4 v[170:171], off
	s_add_i32 m0, s22, 0x2000
	s_add_u32 s16, s16, 0x80080
	v_lshl_add_u64 v[170:171], v[218:219], 0, s[34:35]
	s_addc_u32 s17, s17, 0
	s_add_i32 s22, s66, s77
	global_load_lds_dwordx4 v[170:171], off
	s_mov_b32 m0, s22
	s_nop 0
	global_load_lds_dwordx4 v150, s[16:17]
	s_add_i32 m0, s22, 0x2000
	s_nop 0
	global_load_lds_dwordx4 v146, s[16:17]
	v_lshl_add_u64 v[170:171], v[220:221], 0, s[34:35]
	s_mov_b32 m0, s81
	s_nop 0
	global_load_lds_dwordx4 v[170:171], off
	v_lshl_add_u64 v[170:171], v[222:223], 0, s[34:35]
	s_mov_b32 m0, s60
	s_nop 0
	global_load_lds_dwordx4 v[170:171], off
	s_waitcnt vmcnt(8)
	s_waitcnt lgkmcnt(0)
	s_setprio 1
	s_barrier
	v_mfma_f32_16x16x32_bf16 v[62:65], v[130:133], v[186:189], v[62:65]
	v_mfma_f32_16x16x32_bf16 v[58:61], v[138:141], v[186:189], v[58:61]
	v_mfma_f32_16x16x32_bf16 v[46:49], v[130:133], v[194:197], v[46:49]
	v_mfma_f32_16x16x32_bf16 v[42:45], v[138:141], v[194:197], v[42:45]
	v_mfma_f32_16x16x32_bf16 v[30:33], v[130:133], v[202:205], v[30:33]
	v_mfma_f32_16x16x32_bf16 v[26:29], v[138:141], v[202:205], v[26:29]
	v_mfma_f32_16x16x32_bf16 v[14:17], v[130:133], v[210:213], v[14:17]
	v_mfma_f32_16x16x32_bf16 v[10:13], v[138:141], v[210:213], v[10:13]
	v_mfma_f32_16x16x32_bf16 v[62:65], v[134:137], v[190:193], v[62:65]
	v_mfma_f32_16x16x32_bf16 v[58:61], v[142:145], v[190:193], v[58:61]
	v_mfma_f32_16x16x32_bf16 v[46:49], v[134:137], v[198:201], v[46:49]
	v_mfma_f32_16x16x32_bf16 v[42:45], v[142:145], v[198:201], v[42:45]
	v_mfma_f32_16x16x32_bf16 v[30:33], v[134:137], v[206:209], v[30:33]
	v_mfma_f32_16x16x32_bf16 v[26:29], v[142:145], v[206:209], v[26:29]
	v_mfma_f32_16x16x32_bf16 v[14:17], v[134:137], v[214:217], v[14:17]
	v_mfma_f32_16x16x32_bf16 v[10:13], v[142:145], v[214:217], v[10:13]
	s_setprio 0
	s_setprio 1
	v_mfma_f32_16x16x32_bf16 v[54:57], v[158:161], v[186:189], v[54:57]
	v_mfma_f32_16x16x32_bf16 v[50:53], v[166:169], v[186:189], v[50:53]
	v_mfma_f32_16x16x32_bf16 v[38:41], v[158:161], v[194:197], v[38:41]
	v_mfma_f32_16x16x32_bf16 v[34:37], v[166:169], v[194:197], v[34:37]
	v_mfma_f32_16x16x32_bf16 v[22:25], v[158:161], v[202:205], v[22:25]
	v_mfma_f32_16x16x32_bf16 v[18:21], v[166:169], v[202:205], v[18:21]
	v_mfma_f32_16x16x32_bf16 v[6:9], v[158:161], v[210:213], v[6:9]
	v_mfma_f32_16x16x32_bf16 v[2:5], v[166:169], v[210:213], v[2:5]
	v_mfma_f32_16x16x32_bf16 v[54:57], v[162:165], v[190:193], v[54:57]
	v_mfma_f32_16x16x32_bf16 v[50:53], v[182:185], v[190:193], v[50:53]
	v_mfma_f32_16x16x32_bf16 v[38:41], v[162:165], v[198:201], v[38:41]
	v_mfma_f32_16x16x32_bf16 v[34:37], v[182:185], v[198:201], v[34:37]
	v_mfma_f32_16x16x32_bf16 v[22:25], v[162:165], v[206:209], v[22:25]
	v_mfma_f32_16x16x32_bf16 v[18:21], v[182:185], v[206:209], v[18:21]
	v_mfma_f32_16x16x32_bf16 v[6:9], v[162:165], v[214:217], v[6:9]
	v_mfma_f32_16x16x32_bf16 v[2:5], v[182:185], v[214:217], v[2:5]
	s_barrier
	s_setprio 0
	s_add_i32 s96, s96, 2
	s_add_u32 vcc_lo, vcc_lo, 0x100
	s_addc_u32 vcc_hi, vcc_hi, 0
	s_add_u32 s62, s62, 0x100
	s_addc_u32 s63, s63, 0
	s_cmp_gt_u32 s96, 29
	s_cbranch_scc0 .LBB0_112
	s_and_b64 vcc, exec, s[48:49]
	s_cbranch_vccz .LBB0_115
	s_barrier

.LBB0_288:
	s_add_u32 s24, s50, s90
	s_addc_u32 s26, s51, s91
	s_add_u32 s27, s24, 0x100
	s_addc_u32 s46, s26, 0
	s_and_b64 s[22:23], s[74:75], exec
	s_cselect_b32 vcc_hi, s43, s46
	s_cselect_b32 vcc_lo, s42, s27
	s_add_u32 s22, s48, s90
	s_addc_u32 s23, s49, s91
	s_add_u32 s27, s22, 0x100
	s_addc_u32 s46, s23, 0
	s_add_i32 s63, 0, 0x10000
	s_and_b64 s[22:23], s[74:75], exec
	s_cselect_b32 s75, s19, s46
	s_cselect_b32 s74, s21, s27
	s_add_i32 s66, 0, 0x14000
	s_add_u32 s22, s24, 0x80080
	s_addc_u32 s23, s26, 0
	s_add_i32 s96, s63, s29
	s_add_i32 m0, s56, 0xc000
	s_add_i32 s67, s56, 0xe000
	s_add_i32 s82, s96, 0x2000
	s_add_u32 s90, s74, 0x10000
	v_add_u32_e32 v82, s63, v199
	v_add_u32_e32 v126, s66, v199
	s_addc_u32 s91, s75, 0
	s_add_i32 s89, s66, s29
	ds_read_b128 v[66:69], v82
	ds_read_b128 v[70:73], v82 offset:1024
	ds_read_b128 v[78:81], v82 offset:2048
	ds_read_b128 v[82:85], v82 offset:3072
	ds_read_b128 v[86:89], v126
	ds_read_b128 v[90:93], v126 offset:1024
	ds_read_b128 v[106:109], v126 offset:2048
	ds_read_b128 v[126:129], v126 offset:3072
	s_add_i32 s88, s89, 0x2000
	s_add_i32 s65, 0, 0x18000
	s_add_i32 s64, 0, 0x1c000
	s_add_u32 s26, vcc_lo, 0x80000
	s_addc_u32 s27, vcc_hi, 0
	s_add_i32 s47, s65, s29
	s_add_i32 s46, s47, 0x2000
	s_add_u32 s62, s74, 0x10080
	s_addc_u32 s63, s75, 0
	s_add_i32 s97, s64, s29
	s_add_i32 s24, s97, 0x2000
	ds_read_b128 v[146:149], v201
	ds_read_b128 v[162:165], v201 offset:1024
	ds_read_b128 v[170:173], v201 offset:2048
	ds_read_b128 v[174:177], v201 offset:3072
	ds_read_b128 v[178:181], v201 offset:4096
	ds_read_b128 v[188:191], v201 offset:5120
	ds_read_b128 v[192:195], v201 offset:6144
	ds_read_b128 v[202:205], v201 offset:7168
	global_load_lds_dwordx4 v186, s[22:23]
	s_mov_b32 m0, s67
	s_nop 0
	global_load_lds_dwordx4 v184, s[22:23]
	s_cmp_lg_u32 s100, 0
	s_cbranch_scc1 .Lcw_g2_p1
	s_waitcnt vmcnt(8)
.Lcw_g2_c1:
	s_waitcnt lgkmcnt(0)
	s_setprio 1
	s_barrier
	v_mfma_f32_16x16x32_bf16 v[166:169], v[66:69], v[146:149], v[166:169]
	v_mfma_f32_16x16x32_bf16 v[154:157], v[78:81], v[146:149], v[154:157]
	v_mfma_f32_16x16x32_bf16 v[142:145], v[66:69], v[170:173], v[142:145]
	v_mfma_f32_16x16x32_bf16 v[134:137], v[78:81], v[170:173], v[134:137]
	v_mfma_f32_16x16x32_bf16 v[122:125], v[66:69], v[178:181], v[122:125]
	v_mfma_f32_16x16x32_bf16 v[114:117], v[78:81], v[178:181], v[114:117]
	v_mfma_f32_16x16x32_bf16 v[102:105], v[66:69], v[192:195], v[102:105]
	v_mfma_f32_16x16x32_bf16 v[94:97], v[78:81], v[192:195], v[94:97]
	v_mfma_f32_16x16x32_bf16 v[166:169], v[70:73], v[162:165], v[166:169]
	v_mfma_f32_16x16x32_bf16 v[154:157], v[82:85], v[162:165], v[154:157]
	v_mfma_f32_16x16x32_bf16 v[142:145], v[70:73], v[174:177], v[142:145]
	v_mfma_f32_16x16x32_bf16 v[134:137], v[82:85], v[174:177], v[134:137]
	v_mfma_f32_16x16x32_bf16 v[122:125], v[70:73], v[188:191], v[122:125]
	v_mfma_f32_16x16x32_bf16 v[114:117], v[82:85], v[188:191], v[114:117]
	v_mfma_f32_16x16x32_bf16 v[102:105], v[70:73], v[202:205], v[102:105]
	v_mfma_f32_16x16x32_bf16 v[94:97], v[82:85], v[202:205], v[94:97]
	s_setprio 0
	s_setprio 1
	v_mfma_f32_16x16x32_bf16 v[158:161], v[86:89], v[146:149], v[158:161]
	v_mfma_f32_16x16x32_bf16 v[138:141], v[86:89], v[170:173], v[138:141]
	v_mfma_f32_16x16x32_bf16 v[130:133], v[106:109], v[170:173], v[130:133]
	v_mfma_f32_16x16x32_bf16 v[118:121], v[86:89], v[178:181], v[118:121]
	v_mfma_f32_16x16x32_bf16 v[110:113], v[106:109], v[178:181], v[110:113]
	v_mfma_f32_16x16x32_bf16 v[98:101], v[86:89], v[192:195], v[98:101]
	v_mfma_f32_16x16x32_bf16 v[74:77], v[106:109], v[192:195], v[74:77]
	v_mfma_f32_16x16x32_bf16 v[158:161], v[90:93], v[162:165], v[158:161]
	v_mfma_f32_16x16x32_bf16 v[146:149], v[106:109], v[146:149], v[150:153]
	v_mfma_f32_16x16x32_bf16 v[138:141], v[90:93], v[174:177], v[138:141]
	v_mfma_f32_16x16x32_bf16 v[130:133], v[126:129], v[174:177], v[130:133]
	v_mfma_f32_16x16x32_bf16 v[118:121], v[90:93], v[188:191], v[118:121]
	v_mfma_f32_16x16x32_bf16 v[110:113], v[126:129], v[188:191], v[110:113]
	v_mfma_f32_16x16x32_bf16 v[98:101], v[90:93], v[202:205], v[98:101]
	v_mfma_f32_16x16x32_bf16 v[74:77], v[126:129], v[202:205], v[74:77]
	v_mfma_f32_16x16x32_bf16 v[146:149], v[126:129], v[162:165], v[146:149]
	s_barrier
	s_setprio 0
	s_mov_b32 m0, s96
	v_lshl_add_u64 v[196:197], s[74:75], 0, v[0:1]
	ds_read_b128 v[150:153], v201 offset:16384
	ds_read_b128 v[162:165], v201 offset:17408
	ds_read_b128 v[170:173], v201 offset:18432
	ds_read_b128 v[174:177], v201 offset:19456
	ds_read_b128 v[178:181], v201 offset:20480
	ds_read_b128 v[188:191], v201 offset:21504
	ds_read_b128 v[192:195], v201 offset:22528
	ds_read_b128 v[202:205], v201 offset:23552
	global_load_lds_dwordx4 v[196:197], off
	v_lshl_add_u64 v[206:207], s[74:75], 0, v[182:183]
	s_mov_b32 m0, s82
	v_lshl_add_u64 v[208:209], s[90:91], 0, v[0:1]
	global_load_lds_dwordx4 v[206:207], off
	s_mov_b32 m0, s89
	v_lshl_add_u64 v[210:211], vcc, 0, v[184:185]
	global_load_lds_dwordx4 v[208:209], off
	s_mov_b32 m0, s88
	s_nop 0
	global_load_lds_dwordx4 v182, s[90:91]
	v_lshl_add_u64 v[208:209], vcc, 0, v[186:187]
	s_mov_b32 m0, s56
	s_nop 0
	global_load_lds_dwordx4 v[208:209], off
	s_mov_b32 m0, s57
	s_nop 0
	global_load_lds_dwordx4 v[210:211], off
	s_cmp_lg_u32 s100, 0
	s_cbranch_scc1 .Lcw_g2_p2
	s_waitcnt vmcnt(8)
.Lcw_g2_c2:
	s_waitcnt lgkmcnt(0)
	s_setprio 1
	s_barrier
	v_mfma_f32_16x16x32_bf16 v[62:65], v[66:69], v[150:153], v[62:65]
	v_mfma_f32_16x16x32_bf16 v[54:57], v[78:81], v[150:153], v[54:57]
	v_mfma_f32_16x16x32_bf16 v[46:49], v[66:69], v[170:173], v[46:49]
	v_mfma_f32_16x16x32_bf16 v[38:41], v[78:81], v[170:173], v[38:41]
	v_mfma_f32_16x16x32_bf16 v[30:33], v[66:69], v[178:181], v[30:33]
	v_mfma_f32_16x16x32_bf16 v[22:25], v[78:81], v[178:181], v[22:25]
	v_mfma_f32_16x16x32_bf16 v[14:17], v[66:69], v[192:195], v[14:17]
	v_mfma_f32_16x16x32_bf16 v[6:9], v[78:81], v[192:195], v[6:9]
	v_mfma_f32_16x16x32_bf16 v[62:65], v[70:73], v[162:165], v[62:65]
	v_mfma_f32_16x16x32_bf16 v[54:57], v[82:85], v[162:165], v[54:57]
	v_mfma_f32_16x16x32_bf16 v[46:49], v[70:73], v[174:177], v[46:49]
	v_mfma_f32_16x16x32_bf16 v[38:41], v[82:85], v[174:177], v[38:41]
	v_mfma_f32_16x16x32_bf16 v[30:33], v[70:73], v[188:191], v[30:33]
	v_mfma_f32_16x16x32_bf16 v[22:25], v[82:85], v[188:191], v[22:25]
	v_mfma_f32_16x16x32_bf16 v[14:17], v[70:73], v[202:205], v[14:17]
	v_mfma_f32_16x16x32_bf16 v[6:9], v[82:85], v[202:205], v[6:9]
	s_setprio 0
	s_setprio 1
	v_mfma_f32_16x16x32_bf16 v[58:61], v[86:89], v[150:153], v[58:61]
	v_mfma_f32_16x16x32_bf16 v[50:53], v[106:109], v[150:153], v[50:53]
	v_mfma_f32_16x16x32_bf16 v[42:45], v[86:89], v[170:173], v[42:45]
	v_mfma_f32_16x16x32_bf16 v[34:37], v[106:109], v[170:173], v[34:37]
	v_mfma_f32_16x16x32_bf16 v[26:29], v[86:89], v[178:181], v[26:29]
	v_mfma_f32_16x16x32_bf16 v[18:21], v[106:109], v[178:181], v[18:21]
	v_mfma_f32_16x16x32_bf16 v[10:13], v[86:89], v[192:195], v[10:13]
	v_mfma_f32_16x16x32_bf16 v[2:5], v[106:109], v[192:195], v[2:5]
	v_mfma_f32_16x16x32_bf16 v[58:61], v[90:93], v[162:165], v[58:61]
	v_mfma_f32_16x16x32_bf16 v[50:53], v[126:129], v[162:165], v[50:53]
	v_mfma_f32_16x16x32_bf16 v[42:45], v[90:93], v[174:177], v[42:45]
	v_mfma_f32_16x16x32_bf16 v[34:37], v[126:129], v[174:177], v[34:37]
	v_mfma_f32_16x16x32_bf16 v[26:29], v[90:93], v[188:191], v[26:29]
	v_mfma_f32_16x16x32_bf16 v[18:21], v[126:129], v[188:191], v[18:21]
	v_mfma_f32_16x16x32_bf16 v[10:13], v[90:93], v[202:205], v[10:13]
	v_mfma_f32_16x16x32_bf16 v[2:5], v[126:129], v[202:205], v[2:5]
	s_barrier
	s_setprio 0
	v_add_u32_e32 v82, s65, v199
	v_add_u32_e32 v126, s64, v199
	ds_read_b128 v[66:69], v82
	ds_read_b128 v[70:73], v82 offset:1024
	ds_read_b128 v[78:81], v82 offset:2048
	ds_read_b128 v[82:85], v82 offset:3072
	ds_read_b128 v[86:89], v126
	ds_read_b128 v[90:93], v126 offset:1024
	ds_read_b128 v[106:109], v126 offset:2048
	ds_read_b128 v[126:129], v126 offset:3072
	s_mov_b32 m0, s60
	ds_read_b128 v[150:153], v201 offset:32768
	ds_read_b128 v[162:165], v201 offset:33792
	ds_read_b128 v[170:173], v201 offset:34816
	ds_read_b128 v[174:177], v201 offset:35840
	ds_read_b128 v[178:181], v201 offset:36864
	ds_read_b128 v[188:191], v201 offset:37888
	ds_read_b128 v[192:195], v201 offset:38912
	ds_read_b128 v[202:205], v201 offset:39936
	global_load_lds_dwordx4 v186, s[26:27]
	s_mov_b32 m0, s61
	s_nop 0
	global_load_lds_dwordx4 v184, s[26:27]
	s_waitcnt vmcnt(8)
	s_waitcnt lgkmcnt(0)
	s_setprio 1
	s_barrier
	v_mfma_f32_16x16x32_bf16 v[166:169], v[66:69], v[150:153], v[166:169]
	v_mfma_f32_16x16x32_bf16 v[154:157], v[78:81], v[150:153], v[154:157]
	v_mfma_f32_16x16x32_bf16 v[142:145], v[66:69], v[170:173], v[142:145]
	v_mfma_f32_16x16x32_bf16 v[134:137], v[78:81], v[170:173], v[134:137]
	v_mfma_f32_16x16x32_bf16 v[122:125], v[66:69], v[178:181], v[122:125]
	v_mfma_f32_16x16x32_bf16 v[114:117], v[78:81], v[178:181], v[114:117]
	v_mfma_f32_16x16x32_bf16 v[102:105], v[66:69], v[192:195], v[102:105]
	v_mfma_f32_16x16x32_bf16 v[94:97], v[78:81], v[192:195], v[94:97]
	v_mfma_f32_16x16x32_bf16 v[166:169], v[70:73], v[162:165], v[166:169]
	v_mfma_f32_16x16x32_bf16 v[154:157], v[82:85], v[162:165], v[154:157]
	v_mfma_f32_16x16x32_bf16 v[142:145], v[70:73], v[174:177], v[142:145]
	v_mfma_f32_16x16x32_bf16 v[134:137], v[82:85], v[174:177], v[134:137]
	v_mfma_f32_16x16x32_bf16 v[122:125], v[70:73], v[188:191], v[122:125]
	v_mfma_f32_16x16x32_bf16 v[114:117], v[82:85], v[188:191], v[114:117]
	v_mfma_f32_16x16x32_bf16 v[102:105], v[70:73], v[202:205], v[102:105]
	v_mfma_f32_16x16x32_bf16 v[94:97], v[82:85], v[202:205], v[94:97]
	s_setprio 0
	s_setprio 1
	v_mfma_f32_16x16x32_bf16 v[158:161], v[86:89], v[150:153], v[158:161]
	v_mfma_f32_16x16x32_bf16 v[146:149], v[106:109], v[150:153], v[146:149]
	v_mfma_f32_16x16x32_bf16 v[138:141], v[86:89], v[170:173], v[138:141]
	v_mfma_f32_16x16x32_bf16 v[130:133], v[106:109], v[170:173], v[130:133]
	v_mfma_f32_16x16x32_bf16 v[118:121], v[86:89], v[178:181], v[118:121]
	v_mfma_f32_16x16x32_bf16 v[110:113], v[106:109], v[178:181], v[110:113]
	v_mfma_f32_16x16x32_bf16 v[98:101], v[86:89], v[192:195], v[98:101]
	v_mfma_f32_16x16x32_bf16 v[74:77], v[106:109], v[192:195], v[74:77]
	v_mfma_f32_16x16x32_bf16 v[158:161], v[90:93], v[162:165], v[158:161]
	v_mfma_f32_16x16x32_bf16 v[150:153], v[126:129], v[162:165], v[146:149]
	v_mfma_f32_16x16x32_bf16 v[138:141], v[90:93], v[174:177], v[138:141]
	v_mfma_f32_16x16x32_bf16 v[130:133], v[126:129], v[174:177], v[130:133]
	v_mfma_f32_16x16x32_bf16 v[118:121], v[90:93], v[188:191], v[118:121]
	v_mfma_f32_16x16x32_bf16 v[110:113], v[126:129], v[188:191], v[110:113]
	v_mfma_f32_16x16x32_bf16 v[98:101], v[90:93], v[202:205], v[98:101]
	v_mfma_f32_16x16x32_bf16 v[74:77], v[126:129], v[202:205], v[74:77]
	s_barrier
	s_setprio 0
	s_mov_b32 m0, s47
	v_lshl_add_u64 v[196:197], v[196:197], 0, s[34:35]
	ds_read_b128 v[146:149], v201 offset:49152
	ds_read_b128 v[162:165], v201 offset:50176
	ds_read_b128 v[170:173], v201 offset:51200
	ds_read_b128 v[174:177], v201 offset:52224
	ds_read_b128 v[178:181], v201 offset:53248
	ds_read_b128 v[188:191], v201 offset:54272
	ds_read_b128 v[192:195], v201 offset:55296
	ds_read_b128 v[202:205], v201 offset:56320
	global_load_lds_dwordx4 v[196:197], off
	v_lshl_add_u64 v[196:197], v[206:207], 0, s[34:35]
	s_mov_b32 m0, s46
	s_nop 0
	global_load_lds_dwordx4 v[196:197], off
	v_lshl_add_u64 v[196:197], s[62:63], 0, v[0:1]
	s_mov_b32 m0, s97
	s_nop 0
	global_load_lds_dwordx4 v[196:197], off
	s_mov_b32 m0, s24
	s_nop 0
	global_load_lds_dwordx4 v182, s[62:63]
	v_lshl_add_u64 v[196:197], v[208:209], 0, s[34:35]
	s_mov_b32 m0, s76
	s_nop 0
	global_load_lds_dwordx4 v[196:197], off
	v_lshl_add_u64 v[196:197], v[210:211], 0, s[34:35]
	s_mov_b32 m0, s77
	s_nop 0
	global_load_lds_dwordx4 v[196:197], off
	s_waitcnt vmcnt(8)
	s_waitcnt lgkmcnt(0)
	s_setprio 1
	s_barrier
	v_mfma_f32_16x16x32_bf16 v[62:65], v[66:69], v[146:149], v[62:65]
	v_mfma_f32_16x16x32_bf16 v[54:57], v[78:81], v[146:149], v[54:57]
	v_mfma_f32_16x16x32_bf16 v[46:49], v[66:69], v[170:173], v[46:49]
	v_mfma_f32_16x16x32_bf16 v[38:41], v[78:81], v[170:173], v[38:41]
	v_mfma_f32_16x16x32_bf16 v[30:33], v[66:69], v[178:181], v[30:33]
	v_mfma_f32_16x16x32_bf16 v[22:25], v[78:81], v[178:181], v[22:25]
	v_mfma_f32_16x16x32_bf16 v[14:17], v[66:69], v[192:195], v[14:17]
	v_mfma_f32_16x16x32_bf16 v[6:9], v[78:81], v[192:195], v[6:9]
	v_mfma_f32_16x16x32_bf16 v[62:65], v[70:73], v[162:165], v[62:65]
	v_mfma_f32_16x16x32_bf16 v[54:57], v[82:85], v[162:165], v[54:57]
	v_mfma_f32_16x16x32_bf16 v[46:49], v[70:73], v[174:177], v[46:49]
	v_mfma_f32_16x16x32_bf16 v[38:41], v[82:85], v[174:177], v[38:41]
	v_mfma_f32_16x16x32_bf16 v[30:33], v[70:73], v[188:191], v[30:33]
	v_mfma_f32_16x16x32_bf16 v[22:25], v[82:85], v[188:191], v[22:25]
	v_mfma_f32_16x16x32_bf16 v[14:17], v[70:73], v[202:205], v[14:17]
	v_mfma_f32_16x16x32_bf16 v[6:9], v[82:85], v[202:205], v[6:9]
	s_setprio 0
	s_setprio 1
	v_mfma_f32_16x16x32_bf16 v[58:61], v[86:89], v[146:149], v[58:61]
	v_mfma_f32_16x16x32_bf16 v[50:53], v[106:109], v[146:149], v[50:53]
	v_mfma_f32_16x16x32_bf16 v[42:45], v[86:89], v[170:173], v[42:45]
	v_mfma_f32_16x16x32_bf16 v[34:37], v[106:109], v[170:173], v[34:37]
	v_mfma_f32_16x16x32_bf16 v[26:29], v[86:89], v[178:181], v[26:29]
	v_mfma_f32_16x16x32_bf16 v[18:21], v[106:109], v[178:181], v[18:21]
	v_mfma_f32_16x16x32_bf16 v[10:13], v[86:89], v[192:195], v[10:13]
	v_mfma_f32_16x16x32_bf16 v[2:5], v[106:109], v[192:195], v[2:5]
	v_mfma_f32_16x16x32_bf16 v[58:61], v[90:93], v[162:165], v[58:61]
	v_mfma_f32_16x16x32_bf16 v[50:53], v[126:129], v[162:165], v[50:53]
	v_mfma_f32_16x16x32_bf16 v[42:45], v[90:93], v[174:177], v[42:45]
	v_mfma_f32_16x16x32_bf16 v[34:37], v[126:129], v[174:177], v[34:37]
	v_mfma_f32_16x16x32_bf16 v[26:29], v[90:93], v[188:191], v[26:29]
	v_mfma_f32_16x16x32_bf16 v[18:21], v[126:129], v[188:191], v[18:21]
	v_mfma_f32_16x16x32_bf16 v[10:13], v[90:93], v[202:205], v[10:13]
	v_mfma_f32_16x16x32_bf16 v[2:5], v[126:129], v[202:205], v[2:5]
	s_barrier
	s_setprio 0
	s_andn2_b64 vcc, exec, s[40:41]
	s_mov_b64 s[74:75], -1
	s_mov_b64 s[40:41], 0
	s_mov_b64 s[90:91], 0x100
	s_cbranch_vccz .LBB0_288
	s_and_b64 vcc, exec, s[16:17]
	s_cbranch_vccz .LBB0_291
	s_barrier

.LBB0_526:
	s_add_u32 s22, s13, s20
	s_addc_u32 s23, s15, s21
	s_add_u32 s22, s22, 0x1e800100
	s_addc_u32 s23, s23, 0
	s_add_u32 s24, s40, s20
	s_addc_u32 s26, s41, s21
	s_add_i32 s47, 0, 0x10000
	s_cmpk_eq_i32 s20, 0xf00
	s_cselect_b32 s23, s90, s23
	s_cselect_b32 s22, s89, s22
	s_cselect_b32 s27, s88, s26
	s_cselect_b32 s26, s82, s24
	s_add_i32 s97, 0, 0x14000
	v_add_u32_e32 v233, s47, v230
	v_add_u32_e32 v234, s97, v230
	ds_read_b128 v[134:137], v233
	ds_read_b128 v[138:141], v233 offset:1024
	ds_read_b128 v[142:145], v233 offset:2048
	ds_read_b128 v[146:149], v233 offset:3072
	ds_read_b128 v[150:153], v234
	ds_read_b128 v[154:157], v234 offset:1024
	ds_read_b128 v[158:161], v234 offset:2048
	ds_read_b128 v[162:165], v234 offset:3072
	s_add_i32 s91, s46, 0xc000
	v_lshl_add_u64 v[212:213], v[130:131], 0, s[20:21]
	s_mov_b32 m0, s91
	s_add_i32 s48, s46, 0xe000
	ds_read_b128 v[166:169], v232
	ds_read_b128 v[170:173], v232 offset:1024
	ds_read_b128 v[174:177], v232 offset:2048
	ds_read_b128 v[178:181], v232 offset:3072
	ds_read_b128 v[182:185], v232 offset:4096
	ds_read_b128 v[186:189], v232 offset:5120
	ds_read_b128 v[190:193], v232 offset:6144
	ds_read_b128 v[208:211], v232 offset:7168
	global_load_lds_dwordx4 v[212:213], off
	v_lshl_add_u64 v[212:213], v[132:133], 0, s[20:21]
	s_mov_b32 m0, s48
	s_nop 0
	global_load_lds_dwordx4 v[212:213], off
	s_waitcnt vmcnt(8)
	s_waitcnt lgkmcnt(0)
	s_setprio 1
	s_barrier
	v_mfma_f32_16x16x32_bf16 v[94:97], v[134:137], v[166:169], v[94:97]
	v_mfma_f32_16x16x32_bf16 v[102:105], v[142:145], v[166:169], v[102:105]
	v_mfma_f32_16x16x32_bf16 v[122:125], v[134:137], v[174:177], v[122:125]
	v_mfma_f32_16x16x32_bf16 v[126:129], v[142:145], v[174:177], v[126:129]
	v_mfma_f32_16x16x32_bf16 v[106:109], v[134:137], v[182:185], v[106:109]
	v_mfma_f32_16x16x32_bf16 v[90:93], v[142:145], v[182:185], v[90:93]
	v_mfma_f32_16x16x32_bf16 v[82:85], v[134:137], v[190:193], v[82:85]
	v_mfma_f32_16x16x32_bf16 v[74:77], v[142:145], v[190:193], v[74:77]
	v_mfma_f32_16x16x32_bf16 v[94:97], v[138:141], v[170:173], v[94:97]
	v_mfma_f32_16x16x32_bf16 v[102:105], v[146:149], v[170:173], v[102:105]
	v_mfma_f32_16x16x32_bf16 v[122:125], v[138:141], v[178:181], v[122:125]
	v_mfma_f32_16x16x32_bf16 v[126:129], v[146:149], v[178:181], v[126:129]
	v_mfma_f32_16x16x32_bf16 v[106:109], v[138:141], v[186:189], v[106:109]
	v_mfma_f32_16x16x32_bf16 v[90:93], v[146:149], v[186:189], v[90:93]
	v_mfma_f32_16x16x32_bf16 v[82:85], v[138:141], v[208:211], v[82:85]
	v_mfma_f32_16x16x32_bf16 v[74:77], v[146:149], v[208:211], v[74:77]
	s_setprio 0
	s_setprio 1
	v_mfma_f32_16x16x32_bf16 v[110:113], v[150:153], v[166:169], v[110:113]
	v_mfma_f32_16x16x32_bf16 v[118:121], v[158:161], v[166:169], v[118:121]
	v_mfma_f32_16x16x32_bf16 v[114:117], v[150:153], v[174:177], v[114:117]
	v_mfma_f32_16x16x32_bf16 v[98:101], v[158:161], v[174:177], v[98:101]
	v_mfma_f32_16x16x32_bf16 v[86:89], v[150:153], v[182:185], v[86:89]
	v_mfma_f32_16x16x32_bf16 v[78:81], v[158:161], v[182:185], v[78:81]
	v_mfma_f32_16x16x32_bf16 v[70:73], v[150:153], v[190:193], v[70:73]
	v_mfma_f32_16x16x32_bf16 v[66:69], v[158:161], v[190:193], v[66:69]
	v_mfma_f32_16x16x32_bf16 v[110:113], v[154:157], v[170:173], v[110:113]
	v_mfma_f32_16x16x32_bf16 v[118:121], v[162:165], v[170:173], v[118:121]
	v_mfma_f32_16x16x32_bf16 v[114:117], v[154:157], v[178:181], v[114:117]
	v_mfma_f32_16x16x32_bf16 v[98:101], v[162:165], v[178:181], v[98:101]
	v_mfma_f32_16x16x32_bf16 v[86:89], v[154:157], v[186:189], v[86:89]
	v_mfma_f32_16x16x32_bf16 v[78:81], v[162:165], v[186:189], v[78:81]
	v_mfma_f32_16x16x32_bf16 v[70:73], v[154:157], v[208:211], v[70:73]
	v_mfma_f32_16x16x32_bf16 v[66:69], v[162:165], v[208:211], v[66:69]
	s_barrier
	s_setprio 0
	s_add_i32 s47, s47, s39
	s_add_i32 s96, s47, 0x2000
	v_lshl_add_u64 v[212:213], s[26:27], 0, v[0:1]
	s_mov_b32 m0, s47
	s_add_u32 s36, s26, 0x80000
	ds_read_b128 v[166:169], v232 offset:16384
	ds_read_b128 v[170:173], v232 offset:17408
	ds_read_b128 v[174:177], v232 offset:18432
	ds_read_b128 v[178:181], v232 offset:19456
	ds_read_b128 v[182:185], v232 offset:20480
	ds_read_b128 v[186:189], v232 offset:21504
	ds_read_b128 v[190:193], v232 offset:22528
	ds_read_b128 v[208:211], v232 offset:23552
	global_load_lds_dwordx4 v[212:213], off
	v_lshl_add_u64 v[214:215], s[26:27], 0, v[194:195]
	s_mov_b32 m0, s96
	s_addc_u32 s37, s27, 0
	s_add_i32 s97, s97, s39
	global_load_lds_dwordx4 v[214:215], off
	v_lshl_add_u64 v[216:217], s[36:37], 0, v[0:1]
	s_mov_b32 m0, s97
	v_lshl_add_u64 v[218:219], s[22:23], 0, v[196:197]
	global_load_lds_dwordx4 v[216:217], off
	v_lshl_add_u64 v[216:217], s[36:37], 0, v[194:195]
	s_add_i32 s36, s97, 0x2000
	s_mov_b32 m0, s36
	s_nop 0
	global_load_lds_dwordx4 v[216:217], off
	v_lshl_add_u64 v[216:217], s[22:23], 0, v[198:199]
	s_mov_b32 m0, s46
	s_nop 0
	global_load_lds_dwordx4 v[216:217], off
	s_mov_b32 m0, s49
	s_nop 0
	global_load_lds_dwordx4 v[218:219], off
	s_waitcnt vmcnt(8)
	s_waitcnt lgkmcnt(0)
	s_setprio 1
	s_barrier
	v_mfma_f32_16x16x32_bf16 v[62:65], v[134:137], v[166:169], v[62:65]
	v_mfma_f32_16x16x32_bf16 v[58:61], v[142:145], v[166:169], v[58:61]
	v_mfma_f32_16x16x32_bf16 v[50:53], v[134:137], v[174:177], v[50:53]
	v_mfma_f32_16x16x32_bf16 v[42:45], v[142:145], v[174:177], v[42:45]
	v_mfma_f32_16x16x32_bf16 v[34:37], v[134:137], v[182:185], v[34:37]
	v_mfma_f32_16x16x32_bf16 v[26:29], v[142:145], v[182:185], v[26:29]
	v_mfma_f32_16x16x32_bf16 v[18:21], v[134:137], v[190:193], v[18:21]
	v_mfma_f32_16x16x32_bf16 v[10:13], v[142:145], v[190:193], v[10:13]
	v_mfma_f32_16x16x32_bf16 v[62:65], v[138:141], v[170:173], v[62:65]
	v_mfma_f32_16x16x32_bf16 v[58:61], v[146:149], v[170:173], v[58:61]
	v_mfma_f32_16x16x32_bf16 v[50:53], v[138:141], v[178:181], v[50:53]
	v_mfma_f32_16x16x32_bf16 v[42:45], v[146:149], v[178:181], v[42:45]
	v_mfma_f32_16x16x32_bf16 v[34:37], v[138:141], v[186:189], v[34:37]
	v_mfma_f32_16x16x32_bf16 v[26:29], v[146:149], v[186:189], v[26:29]
	v_mfma_f32_16x16x32_bf16 v[18:21], v[138:141], v[208:211], v[18:21]
	v_mfma_f32_16x16x32_bf16 v[10:13], v[146:149], v[208:211], v[10:13]
	s_setprio 0
	s_setprio 1
	v_mfma_f32_16x16x32_bf16 v[54:57], v[150:153], v[166:169], v[54:57]
	v_mfma_f32_16x16x32_bf16 v[46:49], v[158:161], v[166:169], v[46:49]
	v_mfma_f32_16x16x32_bf16 v[38:41], v[150:153], v[174:177], v[38:41]
	v_mfma_f32_16x16x32_bf16 v[30:33], v[158:161], v[174:177], v[30:33]
	v_mfma_f32_16x16x32_bf16 v[22:25], v[150:153], v[182:185], v[22:25]
	v_mfma_f32_16x16x32_bf16 v[14:17], v[158:161], v[182:185], v[14:17]
	v_mfma_f32_16x16x32_bf16 v[6:9], v[150:153], v[190:193], v[6:9]
	v_mfma_f32_16x16x32_bf16 v[2:5], v[158:161], v[190:193], v[2:5]
	v_mfma_f32_16x16x32_bf16 v[54:57], v[154:157], v[170:173], v[54:57]
	v_mfma_f32_16x16x32_bf16 v[46:49], v[162:165], v[170:173], v[46:49]
	v_mfma_f32_16x16x32_bf16 v[38:41], v[154:157], v[178:181], v[38:41]
	v_mfma_f32_16x16x32_bf16 v[30:33], v[162:165], v[178:181], v[30:33]
	v_mfma_f32_16x16x32_bf16 v[22:25], v[154:157], v[186:189], v[22:25]
	v_mfma_f32_16x16x32_bf16 v[14:17], v[162:165], v[186:189], v[14:17]
	v_mfma_f32_16x16x32_bf16 v[6:9], v[154:157], v[208:211], v[6:9]
	v_mfma_f32_16x16x32_bf16 v[2:5], v[162:165], v[208:211], v[2:5]
	s_barrier
	s_setprio 0
	s_add_i32 s37, 0, 0x18000
	s_add_i32 s24, 0, 0x1c000
	v_add_u32_e32 v235, s37, v230
	v_add_u32_e32 v236, s24, v230
	ds_read_b128 v[134:137], v235
	ds_read_b128 v[138:141], v235 offset:1024
	ds_read_b128 v[142:145], v235 offset:2048
	ds_read_b128 v[146:149], v235 offset:3072
	ds_read_b128 v[150:153], v236
	ds_read_b128 v[154:157], v236 offset:1024
	ds_read_b128 v[158:161], v236 offset:2048
	ds_read_b128 v[162:165], v236 offset:3072
	s_add_u32 s22, s22, 0x80000
	s_addc_u32 s23, s23, 0
	s_mov_b32 m0, s50
	ds_read_b128 v[166:169], v232 offset:32768
	ds_read_b128 v[170:173], v232 offset:33792
	ds_read_b128 v[174:177], v232 offset:34816
	ds_read_b128 v[178:181], v232 offset:35840
	ds_read_b128 v[182:185], v232 offset:36864
	ds_read_b128 v[186:189], v232 offset:37888
	ds_read_b128 v[190:193], v232 offset:38912
	ds_read_b128 v[208:211], v232 offset:39936
	global_load_lds_dwordx4 v198, s[22:23]
	s_mov_b32 m0, s51
	s_nop 0
	global_load_lds_dwordx4 v196, s[22:23]
	s_waitcnt vmcnt(8)
	s_waitcnt lgkmcnt(0)
	s_setprio 1
	s_barrier
	v_mfma_f32_16x16x32_bf16 v[94:97], v[134:137], v[166:169], v[94:97]
	v_mfma_f32_16x16x32_bf16 v[102:105], v[142:145], v[166:169], v[102:105]
	v_mfma_f32_16x16x32_bf16 v[122:125], v[134:137], v[174:177], v[122:125]
	v_mfma_f32_16x16x32_bf16 v[126:129], v[142:145], v[174:177], v[126:129]
	v_mfma_f32_16x16x32_bf16 v[106:109], v[134:137], v[182:185], v[106:109]
	v_mfma_f32_16x16x32_bf16 v[90:93], v[142:145], v[182:185], v[90:93]
	v_mfma_f32_16x16x32_bf16 v[82:85], v[134:137], v[190:193], v[82:85]
	v_mfma_f32_16x16x32_bf16 v[74:77], v[142:145], v[190:193], v[74:77]
	v_mfma_f32_16x16x32_bf16 v[94:97], v[138:141], v[170:173], v[94:97]
	v_mfma_f32_16x16x32_bf16 v[102:105], v[146:149], v[170:173], v[102:105]
	v_mfma_f32_16x16x32_bf16 v[122:125], v[138:141], v[178:181], v[122:125]
	v_mfma_f32_16x16x32_bf16 v[126:129], v[146:149], v[178:181], v[126:129]
	v_mfma_f32_16x16x32_bf16 v[106:109], v[138:141], v[186:189], v[106:109]
	v_mfma_f32_16x16x32_bf16 v[90:93], v[146:149], v[186:189], v[90:93]
	v_mfma_f32_16x16x32_bf16 v[82:85], v[138:141], v[208:211], v[82:85]
	v_mfma_f32_16x16x32_bf16 v[74:77], v[146:149], v[208:211], v[74:77]
	s_setprio 0
	s_setprio 1
	v_mfma_f32_16x16x32_bf16 v[110:113], v[150:153], v[166:169], v[110:113]
	v_mfma_f32_16x16x32_bf16 v[118:121], v[158:161], v[166:169], v[118:121]
	v_mfma_f32_16x16x32_bf16 v[114:117], v[150:153], v[174:177], v[114:117]
	v_mfma_f32_16x16x32_bf16 v[98:101], v[158:161], v[174:177], v[98:101]
	v_mfma_f32_16x16x32_bf16 v[86:89], v[150:153], v[182:185], v[86:89]
	v_mfma_f32_16x16x32_bf16 v[78:81], v[158:161], v[182:185], v[78:81]
	v_mfma_f32_16x16x32_bf16 v[70:73], v[150:153], v[190:193], v[70:73]
	v_mfma_f32_16x16x32_bf16 v[66:69], v[158:161], v[190:193], v[66:69]
	v_mfma_f32_16x16x32_bf16 v[110:113], v[154:157], v[170:173], v[110:113]
	v_mfma_f32_16x16x32_bf16 v[118:121], v[162:165], v[170:173], v[118:121]
	v_mfma_f32_16x16x32_bf16 v[114:117], v[154:157], v[178:181], v[114:117]
	v_mfma_f32_16x16x32_bf16 v[98:101], v[162:165], v[178:181], v[98:101]
	v_mfma_f32_16x16x32_bf16 v[86:89], v[154:157], v[186:189], v[86:89]
	v_mfma_f32_16x16x32_bf16 v[78:81], v[162:165], v[186:189], v[78:81]
	v_mfma_f32_16x16x32_bf16 v[70:73], v[154:157], v[208:211], v[70:73]
	v_mfma_f32_16x16x32_bf16 v[66:69], v[162:165], v[208:211], v[66:69]
	s_barrier
	s_setprio 0
	s_add_i32 s37, s37, s39
	s_add_i32 s64, s37, 0x2000
	v_lshl_add_u64 v[212:213], v[212:213], 0, s[34:35]
	s_mov_b32 m0, s37
	s_add_u32 s22, s26, 0x80080
	ds_read_b128 v[166:169], v232 offset:49152
	ds_read_b128 v[170:173], v232 offset:50176
	ds_read_b128 v[174:177], v232 offset:51200
	ds_read_b128 v[178:181], v232 offset:52224
	ds_read_b128 v[182:185], v232 offset:53248
	ds_read_b128 v[186:189], v232 offset:54272
	ds_read_b128 v[190:193], v232 offset:55296
	ds_read_b128 v[208:211], v232 offset:56320
	global_load_lds_dwordx4 v[212:213], off
	v_lshl_add_u64 v[212:213], v[214:215], 0, s[34:35]
	s_mov_b32 m0, s64
	s_addc_u32 s23, s27, 0
	s_add_i32 s26, s24, s39
	global_load_lds_dwordx4 v[212:213], off
	v_lshl_add_u64 v[212:213], s[22:23], 0, v[0:1]
	s_mov_b32 m0, s26
	s_add_i32 s27, s26, 0x2000
	global_load_lds_dwordx4 v[212:213], off
	s_mov_b32 m0, s27
	s_nop 0
	global_load_lds_dwordx4 v194, s[22:23]
	v_lshl_add_u64 v[212:213], v[216:217], 0, s[34:35]
	s_mov_b32 m0, s62
	s_nop 0
	global_load_lds_dwordx4 v[212:213], off
	v_lshl_add_u64 v[212:213], v[218:219], 0, s[34:35]
	s_mov_b32 m0, s63
	s_nop 0
	global_load_lds_dwordx4 v[212:213], off
	s_waitcnt vmcnt(8)
	s_waitcnt lgkmcnt(0)
	s_setprio 1
	s_barrier
	v_mfma_f32_16x16x32_bf16 v[62:65], v[134:137], v[166:169], v[62:65]
	v_mfma_f32_16x16x32_bf16 v[58:61], v[142:145], v[166:169], v[58:61]
	v_mfma_f32_16x16x32_bf16 v[50:53], v[134:137], v[174:177], v[50:53]
	v_mfma_f32_16x16x32_bf16 v[42:45], v[142:145], v[174:177], v[42:45]
	v_mfma_f32_16x16x32_bf16 v[34:37], v[134:137], v[182:185], v[34:37]
	v_mfma_f32_16x16x32_bf16 v[26:29], v[142:145], v[182:185], v[26:29]
	v_mfma_f32_16x16x32_bf16 v[18:21], v[134:137], v[190:193], v[18:21]
	v_mfma_f32_16x16x32_bf16 v[10:13], v[142:145], v[190:193], v[10:13]
	v_mfma_f32_16x16x32_bf16 v[62:65], v[138:141], v[170:173], v[62:65]
	v_mfma_f32_16x16x32_bf16 v[58:61], v[146:149], v[170:173], v[58:61]
	v_mfma_f32_16x16x32_bf16 v[50:53], v[138:141], v[178:181], v[50:53]
	v_mfma_f32_16x16x32_bf16 v[42:45], v[146:149], v[178:181], v[42:45]
	v_mfma_f32_16x16x32_bf16 v[34:37], v[138:141], v[186:189], v[34:37]
	v_mfma_f32_16x16x32_bf16 v[26:29], v[146:149], v[186:189], v[26:29]
	v_mfma_f32_16x16x32_bf16 v[18:21], v[138:141], v[208:211], v[18:21]
	v_mfma_f32_16x16x32_bf16 v[10:13], v[146:149], v[208:211], v[10:13]
	s_setprio 0
	s_setprio 1
	v_mfma_f32_16x16x32_bf16 v[54:57], v[150:153], v[166:169], v[54:57]
	v_mfma_f32_16x16x32_bf16 v[46:49], v[158:161], v[166:169], v[46:49]
	v_mfma_f32_16x16x32_bf16 v[38:41], v[150:153], v[174:177], v[38:41]
	v_mfma_f32_16x16x32_bf16 v[30:33], v[158:161], v[174:177], v[30:33]
	v_mfma_f32_16x16x32_bf16 v[22:25], v[150:153], v[182:185], v[22:25]
	v_mfma_f32_16x16x32_bf16 v[14:17], v[158:161], v[182:185], v[14:17]
	v_mfma_f32_16x16x32_bf16 v[6:9], v[150:153], v[190:193], v[6:9]
	v_mfma_f32_16x16x32_bf16 v[2:5], v[158:161], v[190:193], v[2:5]
	v_mfma_f32_16x16x32_bf16 v[54:57], v[154:157], v[170:173], v[54:57]
	v_mfma_f32_16x16x32_bf16 v[46:49], v[162:165], v[170:173], v[46:49]
	v_mfma_f32_16x16x32_bf16 v[38:41], v[154:157], v[178:181], v[38:41]
	v_mfma_f32_16x16x32_bf16 v[30:33], v[162:165], v[178:181], v[30:33]
	v_mfma_f32_16x16x32_bf16 v[22:25], v[154:157], v[186:189], v[22:25]
	v_mfma_f32_16x16x32_bf16 v[14:17], v[162:165], v[186:189], v[14:17]
	v_mfma_f32_16x16x32_bf16 v[6:9], v[154:157], v[208:211], v[6:9]
	v_mfma_f32_16x16x32_bf16 v[2:5], v[162:165], v[208:211], v[2:5]
	s_barrier
	s_setprio 0
	s_add_i32 s42, s42, 2
	s_add_u32 s20, s20, 0x100
	s_addc_u32 s21, s21, 0
	s_cmp_gt_u32 s42, 29
	s_cbranch_scc0 .LBB0_526
	s_and_b64 vcc, exec, s[10:11]
	s_cbranch_vccz .LBB0_529
	s_barrier

.LBB0_646:
	s_add_u32 s22, s90, 0xfff80080
	s_addc_u32 s23, s91, -1
	s_add_i32 s24, 0, 0x10000
	s_cmp_eq_u32 s47, 28
	s_cselect_b32 s23, s9, s23
	s_cselect_b32 s22, s21, s22
	s_cselect_b32 s27, s19, s46
	s_cselect_b32 s26, s36, s37
	s_add_i32 s64, 0, 0x14000
	v_add_u32_e32 v142, s24, v225
	v_add_u32_e32 v158, s64, v225
	ds_read_b128 v[130:133], v142
	ds_read_b128 v[134:137], v142 offset:1024
	ds_read_b128 v[138:141], v142 offset:2048
	ds_read_b128 v[142:145], v142 offset:3072
	ds_read_b128 v[146:149], v158
	ds_read_b128 v[150:153], v158 offset:1024
	ds_read_b128 v[154:157], v158 offset:2048
	ds_read_b128 v[158:161], v158 offset:3072
	s_add_i32 m0, s56, 0xc000
	ds_read_b128 v[162:165], v232
	ds_read_b128 v[166:169], v232 offset:1024
	ds_read_b128 v[170:173], v232 offset:2048
	ds_read_b128 v[174:177], v232 offset:3072
	ds_read_b128 v[178:181], v232 offset:4096
	ds_read_b128 v[182:185], v232 offset:5120
	ds_read_b128 v[186:189], v232 offset:6144
	ds_read_b128 v[190:193], v232 offset:7168
	global_load_lds_dwordx4 v200, s[90:91]
	s_add_i32 m0, s56, 0xe000
	s_nop 0
	global_load_lds_dwordx4 v202, s[90:91]
	s_waitcnt vmcnt(8)
	s_waitcnt lgkmcnt(0)
	s_setprio 1
	s_barrier
	v_mfma_f32_16x16x32_bf16 v[126:129], v[130:133], v[162:165], v[126:129]
	v_mfma_f32_16x16x32_bf16 v[122:125], v[138:141], v[162:165], v[122:125]
	v_mfma_f32_16x16x32_bf16 v[110:113], v[130:133], v[170:173], v[110:113]
	v_mfma_f32_16x16x32_bf16 v[106:109], v[138:141], v[170:173], v[106:109]
	v_mfma_f32_16x16x32_bf16 v[94:97], v[130:133], v[178:181], v[94:97]
	v_mfma_f32_16x16x32_bf16 v[90:93], v[138:141], v[178:181], v[90:93]
	v_mfma_f32_16x16x32_bf16 v[78:81], v[130:133], v[186:189], v[78:81]
	v_mfma_f32_16x16x32_bf16 v[74:77], v[138:141], v[186:189], v[74:77]
	v_mfma_f32_16x16x32_bf16 v[126:129], v[134:137], v[166:169], v[126:129]
	v_mfma_f32_16x16x32_bf16 v[122:125], v[142:145], v[166:169], v[122:125]
	v_mfma_f32_16x16x32_bf16 v[110:113], v[134:137], v[174:177], v[110:113]
	v_mfma_f32_16x16x32_bf16 v[106:109], v[142:145], v[174:177], v[106:109]
	v_mfma_f32_16x16x32_bf16 v[94:97], v[134:137], v[182:185], v[94:97]
	v_mfma_f32_16x16x32_bf16 v[90:93], v[142:145], v[182:185], v[90:93]
	v_mfma_f32_16x16x32_bf16 v[78:81], v[134:137], v[190:193], v[78:81]
	v_mfma_f32_16x16x32_bf16 v[74:77], v[142:145], v[190:193], v[74:77]
	s_setprio 0
	s_setprio 1
	v_mfma_f32_16x16x32_bf16 v[118:121], v[146:149], v[162:165], v[118:121]
	v_mfma_f32_16x16x32_bf16 v[114:117], v[154:157], v[162:165], v[114:117]
	v_mfma_f32_16x16x32_bf16 v[102:105], v[146:149], v[170:173], v[102:105]
	v_mfma_f32_16x16x32_bf16 v[98:101], v[154:157], v[170:173], v[98:101]
	v_mfma_f32_16x16x32_bf16 v[86:89], v[146:149], v[178:181], v[86:89]
	v_mfma_f32_16x16x32_bf16 v[82:85], v[154:157], v[178:181], v[82:85]
	v_mfma_f32_16x16x32_bf16 v[70:73], v[146:149], v[186:189], v[70:73]
	v_mfma_f32_16x16x32_bf16 v[66:69], v[154:157], v[186:189], v[66:69]
	v_mfma_f32_16x16x32_bf16 v[118:121], v[150:153], v[166:169], v[118:121]
	v_mfma_f32_16x16x32_bf16 v[114:117], v[158:161], v[166:169], v[114:117]
	v_mfma_f32_16x16x32_bf16 v[102:105], v[150:153], v[174:177], v[102:105]
	v_mfma_f32_16x16x32_bf16 v[98:101], v[158:161], v[174:177], v[98:101]
	v_mfma_f32_16x16x32_bf16 v[86:89], v[150:153], v[182:185], v[86:89]
	v_mfma_f32_16x16x32_bf16 v[82:85], v[158:161], v[182:185], v[82:85]
	v_mfma_f32_16x16x32_bf16 v[70:73], v[150:153], v[190:193], v[70:73]
	v_mfma_f32_16x16x32_bf16 v[66:69], v[158:161], v[190:193], v[66:69]
	s_barrier
	s_setprio 0
	s_add_i32 s24, s24, s25
	v_lshl_add_u64 v[204:205], s[26:27], 0, v[0:1]
	s_mov_b32 m0, s24
	ds_read_b128 v[162:165], v232 offset:16384
	ds_read_b128 v[166:169], v232 offset:17408
	ds_read_b128 v[170:173], v232 offset:18432
	ds_read_b128 v[174:177], v232 offset:19456
	ds_read_b128 v[178:181], v232 offset:20480
	ds_read_b128 v[182:185], v232 offset:21504
	ds_read_b128 v[186:189], v232 offset:22528
	ds_read_b128 v[190:193], v232 offset:23552
	global_load_lds_dwordx4 v[204:205], off
	s_add_i32 m0, s24, 0x2000
	s_add_u32 s50, s26, 0x80000
	v_lshl_add_u64 v[206:207], s[26:27], 0, v[198:199]
	s_addc_u32 s51, s27, 0
	s_add_i32 s24, s64, s25
	global_load_lds_dwordx4 v[206:207], off
	v_lshl_add_u64 v[208:209], s[50:51], 0, v[0:1]
	s_mov_b32 m0, s24
	v_lshl_add_u64 v[210:211], s[22:23], 0, v[196:197]
	global_load_lds_dwordx4 v[208:209], off
	s_add_i32 m0, s24, 0x2000
	s_nop 0
	global_load_lds_dwordx4 v198, s[50:51]
	v_lshl_add_u64 v[208:209], s[22:23], 0, v[194:195]
	s_mov_b32 m0, s56
	s_nop 0
	global_load_lds_dwordx4 v[208:209], off
	s_mov_b32 m0, s57
	s_nop 0
	global_load_lds_dwordx4 v[210:211], off
	s_waitcnt vmcnt(8)
	s_waitcnt lgkmcnt(0)
	s_setprio 1
	s_barrier
	v_mfma_f32_16x16x32_bf16 v[62:65], v[130:133], v[162:165], v[62:65]
	v_mfma_f32_16x16x32_bf16 v[58:61], v[138:141], v[162:165], v[58:61]
	v_mfma_f32_16x16x32_bf16 v[46:49], v[130:133], v[170:173], v[46:49]
	v_mfma_f32_16x16x32_bf16 v[42:45], v[138:141], v[170:173], v[42:45]
	v_mfma_f32_16x16x32_bf16 v[30:33], v[130:133], v[178:181], v[30:33]
	v_mfma_f32_16x16x32_bf16 v[26:29], v[138:141], v[178:181], v[26:29]
	v_mfma_f32_16x16x32_bf16 v[14:17], v[130:133], v[186:189], v[14:17]
	v_mfma_f32_16x16x32_bf16 v[10:13], v[138:141], v[186:189], v[10:13]
	v_mfma_f32_16x16x32_bf16 v[62:65], v[134:137], v[166:169], v[62:65]
	v_mfma_f32_16x16x32_bf16 v[58:61], v[142:145], v[166:169], v[58:61]
	v_mfma_f32_16x16x32_bf16 v[46:49], v[134:137], v[174:177], v[46:49]
	v_mfma_f32_16x16x32_bf16 v[42:45], v[142:145], v[174:177], v[42:45]
	v_mfma_f32_16x16x32_bf16 v[30:33], v[134:137], v[182:185], v[30:33]
	v_mfma_f32_16x16x32_bf16 v[26:29], v[142:145], v[182:185], v[26:29]
	v_mfma_f32_16x16x32_bf16 v[14:17], v[134:137], v[190:193], v[14:17]
	v_mfma_f32_16x16x32_bf16 v[10:13], v[142:145], v[190:193], v[10:13]
	s_setprio 0
	s_setprio 1
	v_mfma_f32_16x16x32_bf16 v[54:57], v[146:149], v[162:165], v[54:57]
	v_mfma_f32_16x16x32_bf16 v[50:53], v[154:157], v[162:165], v[50:53]
	v_mfma_f32_16x16x32_bf16 v[38:41], v[146:149], v[170:173], v[38:41]
	v_mfma_f32_16x16x32_bf16 v[34:37], v[154:157], v[170:173], v[34:37]
	v_mfma_f32_16x16x32_bf16 v[22:25], v[146:149], v[178:181], v[22:25]
	v_mfma_f32_16x16x32_bf16 v[18:21], v[154:157], v[178:181], v[18:21]
	v_mfma_f32_16x16x32_bf16 v[6:9], v[146:149], v[186:189], v[6:9]
	v_mfma_f32_16x16x32_bf16 v[2:5], v[154:157], v[186:189], v[2:5]
	v_mfma_f32_16x16x32_bf16 v[54:57], v[150:153], v[166:169], v[54:57]
	v_mfma_f32_16x16x32_bf16 v[50:53], v[158:161], v[166:169], v[50:53]
	v_mfma_f32_16x16x32_bf16 v[38:41], v[150:153], v[174:177], v[38:41]
	v_mfma_f32_16x16x32_bf16 v[34:37], v[158:161], v[174:177], v[34:37]
	v_mfma_f32_16x16x32_bf16 v[22:25], v[150:153], v[182:185], v[22:25]
	v_mfma_f32_16x16x32_bf16 v[18:21], v[158:161], v[182:185], v[18:21]
	v_mfma_f32_16x16x32_bf16 v[6:9], v[150:153], v[190:193], v[6:9]
	v_mfma_f32_16x16x32_bf16 v[2:5], v[158:161], v[190:193], v[2:5]
	s_barrier
	s_setprio 0
	s_add_i32 s24, 0, 0x18000
	s_add_i32 s50, 0, 0x1c000
	v_add_u32_e32 v142, s24, v225
	v_add_u32_e32 v158, s50, v225
	ds_read_b128 v[130:133], v142
	ds_read_b128 v[134:137], v142 offset:1024
	ds_read_b128 v[138:141], v142 offset:2048
	ds_read_b128 v[142:145], v142 offset:3072
	ds_read_b128 v[146:149], v158
	ds_read_b128 v[150:153], v158 offset:1024
	ds_read_b128 v[154:157], v158 offset:2048
	ds_read_b128 v[158:161], v158 offset:3072
	s_add_u32 s22, s22, 0x80000
	s_addc_u32 s23, s23, 0
	s_mov_b32 m0, s60
	ds_read_b128 v[162:165], v232 offset:32768
	ds_read_b128 v[166:169], v232 offset:33792
	ds_read_b128 v[170:173], v232 offset:34816
	ds_read_b128 v[174:177], v232 offset:35840
	ds_read_b128 v[178:181], v232 offset:36864
	ds_read_b128 v[182:185], v232 offset:37888
	ds_read_b128 v[186:189], v232 offset:38912
	ds_read_b128 v[190:193], v232 offset:39936
	global_load_lds_dwordx4 v194, s[22:23]
	s_mov_b32 m0, s61
	s_nop 0
	global_load_lds_dwordx4 v196, s[22:23]
	s_waitcnt vmcnt(8)
	s_waitcnt lgkmcnt(0)
	s_setprio 1
	s_barrier
	v_mfma_f32_16x16x32_bf16 v[126:129], v[130:133], v[162:165], v[126:129]
	v_mfma_f32_16x16x32_bf16 v[122:125], v[138:141], v[162:165], v[122:125]
	v_mfma_f32_16x16x32_bf16 v[110:113], v[130:133], v[170:173], v[110:113]
	v_mfma_f32_16x16x32_bf16 v[106:109], v[138:141], v[170:173], v[106:109]
	v_mfma_f32_16x16x32_bf16 v[94:97], v[130:133], v[178:181], v[94:97]
	v_mfma_f32_16x16x32_bf16 v[90:93], v[138:141], v[178:181], v[90:93]
	v_mfma_f32_16x16x32_bf16 v[78:81], v[130:133], v[186:189], v[78:81]
	v_mfma_f32_16x16x32_bf16 v[74:77], v[138:141], v[186:189], v[74:77]
	v_mfma_f32_16x16x32_bf16 v[126:129], v[134:137], v[166:169], v[126:129]
	v_mfma_f32_16x16x32_bf16 v[122:125], v[142:145], v[166:169], v[122:125]
	v_mfma_f32_16x16x32_bf16 v[110:113], v[134:137], v[174:177], v[110:113]
	v_mfma_f32_16x16x32_bf16 v[106:109], v[142:145], v[174:177], v[106:109]
	v_mfma_f32_16x16x32_bf16 v[94:97], v[134:137], v[182:185], v[94:97]
	v_mfma_f32_16x16x32_bf16 v[90:93], v[142:145], v[182:185], v[90:93]
	v_mfma_f32_16x16x32_bf16 v[78:81], v[134:137], v[190:193], v[78:81]
	v_mfma_f32_16x16x32_bf16 v[74:77], v[142:145], v[190:193], v[74:77]
	s_setprio 0
	s_setprio 1
	v_mfma_f32_16x16x32_bf16 v[118:121], v[146:149], v[162:165], v[118:121]
	v_mfma_f32_16x16x32_bf16 v[114:117], v[154:157], v[162:165], v[114:117]
	v_mfma_f32_16x16x32_bf16 v[102:105], v[146:149], v[170:173], v[102:105]
	v_mfma_f32_16x16x32_bf16 v[98:101], v[154:157], v[170:173], v[98:101]
	v_mfma_f32_16x16x32_bf16 v[86:89], v[146:149], v[178:181], v[86:89]
	v_mfma_f32_16x16x32_bf16 v[82:85], v[154:157], v[178:181], v[82:85]
	v_mfma_f32_16x16x32_bf16 v[70:73], v[146:149], v[186:189], v[70:73]
	v_mfma_f32_16x16x32_bf16 v[66:69], v[154:157], v[186:189], v[66:69]
	v_mfma_f32_16x16x32_bf16 v[118:121], v[150:153], v[166:169], v[118:121]
	v_mfma_f32_16x16x32_bf16 v[114:117], v[158:161], v[166:169], v[114:117]
	v_mfma_f32_16x16x32_bf16 v[102:105], v[150:153], v[174:177], v[102:105]
	v_mfma_f32_16x16x32_bf16 v[98:101], v[158:161], v[174:177], v[98:101]
	v_mfma_f32_16x16x32_bf16 v[86:89], v[150:153], v[182:185], v[86:89]
	v_mfma_f32_16x16x32_bf16 v[82:85], v[158:161], v[182:185], v[82:85]
	v_mfma_f32_16x16x32_bf16 v[70:73], v[150:153], v[190:193], v[70:73]
	v_mfma_f32_16x16x32_bf16 v[66:69], v[158:161], v[190:193], v[66:69]
	s_barrier
	s_setprio 0
	s_add_i32 s22, s24, s25
	v_lshl_add_u64 v[204:205], v[204:205], 0, s[34:35]
	s_mov_b32 m0, s22
	ds_read_b128 v[162:165], v232 offset:49152
	ds_read_b128 v[166:169], v232 offset:50176
	ds_read_b128 v[170:173], v232 offset:51200
	ds_read_b128 v[174:177], v232 offset:52224
	ds_read_b128 v[178:181], v232 offset:53248
	ds_read_b128 v[182:185], v232 offset:54272
	ds_read_b128 v[186:189], v232 offset:55296
	ds_read_b128 v[190:193], v232 offset:56320
	global_load_lds_dwordx4 v[204:205], off
	s_add_i32 m0, s22, 0x2000
	s_add_u32 s22, s26, 0x80080
	v_lshl_add_u64 v[204:205], v[206:207], 0, s[34:35]
	s_addc_u32 s23, s27, 0
	s_add_i32 s24, s50, s25
	global_load_lds_dwordx4 v[204:205], off
	v_lshl_add_u64 v[204:205], s[22:23], 0, v[0:1]
	s_mov_b32 m0, s24
	s_nop 0
	global_load_lds_dwordx4 v[204:205], off
	s_add_i32 m0, s24, 0x2000
	s_nop 0
	global_load_lds_dwordx4 v198, s[22:23]
	v_lshl_add_u64 v[204:205], v[208:209], 0, s[34:35]
	s_mov_b32 m0, s75
	s_nop 0
	global_load_lds_dwordx4 v[204:205], off
	v_lshl_add_u64 v[204:205], v[210:211], 0, s[34:35]
	s_mov_b32 m0, s76
	s_nop 0
	global_load_lds_dwordx4 v[204:205], off
	s_waitcnt vmcnt(8)
	s_waitcnt lgkmcnt(0)
	s_setprio 1
	s_barrier
	v_mfma_f32_16x16x32_bf16 v[62:65], v[130:133], v[162:165], v[62:65]
	v_mfma_f32_16x16x32_bf16 v[58:61], v[138:141], v[162:165], v[58:61]
	v_mfma_f32_16x16x32_bf16 v[46:49], v[130:133], v[170:173], v[46:49]
	v_mfma_f32_16x16x32_bf16 v[42:45], v[138:141], v[170:173], v[42:45]
	v_mfma_f32_16x16x32_bf16 v[30:33], v[130:133], v[178:181], v[30:33]
	v_mfma_f32_16x16x32_bf16 v[26:29], v[138:141], v[178:181], v[26:29]
	v_mfma_f32_16x16x32_bf16 v[14:17], v[130:133], v[186:189], v[14:17]
	v_mfma_f32_16x16x32_bf16 v[10:13], v[138:141], v[186:189], v[10:13]
	v_mfma_f32_16x16x32_bf16 v[62:65], v[134:137], v[166:169], v[62:65]
	v_mfma_f32_16x16x32_bf16 v[58:61], v[142:145], v[166:169], v[58:61]
	v_mfma_f32_16x16x32_bf16 v[46:49], v[134:137], v[174:177], v[46:49]
	v_mfma_f32_16x16x32_bf16 v[42:45], v[142:145], v[174:177], v[42:45]
	v_mfma_f32_16x16x32_bf16 v[30:33], v[134:137], v[182:185], v[30:33]
	v_mfma_f32_16x16x32_bf16 v[26:29], v[142:145], v[182:185], v[26:29]
	v_mfma_f32_16x16x32_bf16 v[14:17], v[134:137], v[190:193], v[14:17]
	v_mfma_f32_16x16x32_bf16 v[10:13], v[142:145], v[190:193], v[10:13]
	s_setprio 0
	s_setprio 1
	v_mfma_f32_16x16x32_bf16 v[54:57], v[146:149], v[162:165], v[54:57]
	v_mfma_f32_16x16x32_bf16 v[50:53], v[154:157], v[162:165], v[50:53]
	v_mfma_f32_16x16x32_bf16 v[38:41], v[146:149], v[170:173], v[38:41]
	v_mfma_f32_16x16x32_bf16 v[34:37], v[154:157], v[170:173], v[34:37]
	v_mfma_f32_16x16x32_bf16 v[22:25], v[146:149], v[178:181], v[22:25]
	v_mfma_f32_16x16x32_bf16 v[18:21], v[154:157], v[178:181], v[18:21]
	v_mfma_f32_16x16x32_bf16 v[6:9], v[146:149], v[186:189], v[6:9]
	v_mfma_f32_16x16x32_bf16 v[2:5], v[154:157], v[186:189], v[2:5]
	v_mfma_f32_16x16x32_bf16 v[54:57], v[150:153], v[166:169], v[54:57]
	v_mfma_f32_16x16x32_bf16 v[50:53], v[158:161], v[166:169], v[50:53]
	v_mfma_f32_16x16x32_bf16 v[38:41], v[150:153], v[174:177], v[38:41]
	v_mfma_f32_16x16x32_bf16 v[34:37], v[158:161], v[174:177], v[34:37]
	v_mfma_f32_16x16x32_bf16 v[22:25], v[150:153], v[182:185], v[22:25]
	v_mfma_f32_16x16x32_bf16 v[18:21], v[158:161], v[182:185], v[18:21]
	v_mfma_f32_16x16x32_bf16 v[6:9], v[150:153], v[190:193], v[6:9]
	v_mfma_f32_16x16x32_bf16 v[2:5], v[158:161], v[190:193], v[2:5]
	s_barrier
	s_setprio 0
	s_add_i32 s47, s47, 2
	s_add_u32 s90, s90, 0x100
	s_addc_u32 s91, s91, 0
	s_add_u32 s37, s37, 0x100
	s_addc_u32 s46, s46, 0
	s_cmp_gt_u32 s47, 29
	s_cbranch_scc0 .LBB0_646
	s_and_b64 vcc, exec, s[14:15]
	s_cbranch_vccz .LBB0_649
	s_barrier

.LBB0_774:
	s_add_u32 s22, s20, 0xfff80080
	s_addc_u32 s23, s21, -1
	s_add_i32 s24, 0, 0x10000
	s_cmp_eq_u32 s62, 28
	s_cselect_b32 s23, s15, s23
	s_cselect_b32 s22, s60, s22
	s_cselect_b32 s27, s13, s47
	s_cselect_b32 s26, s61, s46
	s_add_i32 s63, 0, 0x14000
	v_add_u32_e32 v160, s24, v153
	v_add_u32_e32 v176, s63, v153
	ds_read_b128 v[140:143], v160
	ds_read_b128 v[144:147], v160 offset:1024
	ds_read_b128 v[148:151], v160 offset:2048
	ds_read_b128 v[160:163], v160 offset:3072
	ds_read_b128 v[164:167], v176
	ds_read_b128 v[168:171], v176 offset:1024
	ds_read_b128 v[172:175], v176 offset:2048
	ds_read_b128 v[176:179], v176 offset:3072
	s_add_i32 m0, s38, 0xc000
	ds_read_b128 v[180:183], v159
	ds_read_b128 v[184:187], v159 offset:1024
	ds_read_b128 v[188:191], v159 offset:2048
	ds_read_b128 v[192:195], v159 offset:3072
	ds_read_b128 v[196:199], v159 offset:4096
	ds_read_b128 v[200:203], v159 offset:5120
	ds_read_b128 v[204:207], v159 offset:6144
	ds_read_b128 v[208:211], v159 offset:7168
	global_load_lds_dwordx4 v136, s[20:21]
	s_add_i32 m0, s38, 0xe000
	s_nop 0
	global_load_lds_dwordx4 v138, s[20:21]
	s_cmp_lg_u32 s100, 0
	s_cbranch_scc1 .Lcw_g6_p1
	s_waitcnt vmcnt(8)
.Lcw_g6_c1:
	s_waitcnt lgkmcnt(0)
	s_setprio 1
	s_barrier
	v_mfma_f32_16x16x32_bf16 v[126:129], v[140:143], v[180:183], v[126:129]
	v_mfma_f32_16x16x32_bf16 v[122:125], v[148:151], v[180:183], v[122:125]
	v_mfma_f32_16x16x32_bf16 v[110:113], v[140:143], v[188:191], v[110:113]
	v_mfma_f32_16x16x32_bf16 v[106:109], v[148:151], v[188:191], v[106:109]
	v_mfma_f32_16x16x32_bf16 v[94:97], v[140:143], v[196:199], v[94:97]
	v_mfma_f32_16x16x32_bf16 v[90:93], v[148:151], v[196:199], v[90:93]
	v_mfma_f32_16x16x32_bf16 v[78:81], v[140:143], v[204:207], v[78:81]
	v_mfma_f32_16x16x32_bf16 v[74:77], v[148:151], v[204:207], v[74:77]
	v_mfma_f32_16x16x32_bf16 v[126:129], v[144:147], v[184:187], v[126:129]
	v_mfma_f32_16x16x32_bf16 v[122:125], v[160:163], v[184:187], v[122:125]
	v_mfma_f32_16x16x32_bf16 v[110:113], v[144:147], v[192:195], v[110:113]
	v_mfma_f32_16x16x32_bf16 v[106:109], v[160:163], v[192:195], v[106:109]
	v_mfma_f32_16x16x32_bf16 v[94:97], v[144:147], v[200:203], v[94:97]
	v_mfma_f32_16x16x32_bf16 v[90:93], v[160:163], v[200:203], v[90:93]
	v_mfma_f32_16x16x32_bf16 v[78:81], v[144:147], v[208:211], v[78:81]
	v_mfma_f32_16x16x32_bf16 v[74:77], v[160:163], v[208:211], v[74:77]
	s_setprio 0
	s_setprio 1
	v_mfma_f32_16x16x32_bf16 v[118:121], v[164:167], v[180:183], v[118:121]
	v_mfma_f32_16x16x32_bf16 v[114:117], v[172:175], v[180:183], v[114:117]
	v_mfma_f32_16x16x32_bf16 v[102:105], v[164:167], v[188:191], v[102:105]
	v_mfma_f32_16x16x32_bf16 v[98:101], v[172:175], v[188:191], v[98:101]
	v_mfma_f32_16x16x32_bf16 v[86:89], v[164:167], v[196:199], v[86:89]
	v_mfma_f32_16x16x32_bf16 v[82:85], v[172:175], v[196:199], v[82:85]
	v_mfma_f32_16x16x32_bf16 v[70:73], v[164:167], v[204:207], v[70:73]
	v_mfma_f32_16x16x32_bf16 v[66:69], v[172:175], v[204:207], v[66:69]
	v_mfma_f32_16x16x32_bf16 v[118:121], v[168:171], v[184:187], v[118:121]
	v_mfma_f32_16x16x32_bf16 v[114:117], v[176:179], v[184:187], v[114:117]
	v_mfma_f32_16x16x32_bf16 v[102:105], v[168:171], v[192:195], v[102:105]
	v_mfma_f32_16x16x32_bf16 v[98:101], v[176:179], v[192:195], v[98:101]
	v_mfma_f32_16x16x32_bf16 v[86:89], v[168:171], v[200:203], v[86:89]
	v_mfma_f32_16x16x32_bf16 v[82:85], v[176:179], v[200:203], v[82:85]
	v_mfma_f32_16x16x32_bf16 v[70:73], v[168:171], v[208:211], v[70:73]
	v_mfma_f32_16x16x32_bf16 v[66:69], v[176:179], v[208:211], v[66:69]
	s_barrier
	s_setprio 0
	s_add_i32 s24, s24, s29
	v_lshl_add_u64 v[212:213], s[26:27], 0, v[0:1]
	s_mov_b32 m0, s24
	ds_read_b128 v[180:183], v159 offset:16384
	ds_read_b128 v[184:187], v159 offset:17408
	ds_read_b128 v[188:191], v159 offset:18432
	ds_read_b128 v[192:195], v159 offset:19456
	ds_read_b128 v[196:199], v159 offset:20480
	ds_read_b128 v[200:203], v159 offset:21504
	ds_read_b128 v[204:207], v159 offset:22528
	ds_read_b128 v[208:211], v159 offset:23552
	global_load_lds_dwordx4 v[212:213], off
	s_add_i32 m0, s24, 0x2000
	s_add_u32 s64, s26, 0x80000
	v_lshl_add_u64 v[214:215], s[26:27], 0, v[130:131]
	s_addc_u32 s65, s27, 0
	s_add_i32 s24, s63, s29
	global_load_lds_dwordx4 v[214:215], off
	v_lshl_add_u64 v[216:217], s[64:65], 0, v[0:1]
	s_mov_b32 m0, s24
	v_lshl_add_u64 v[218:219], s[22:23], 0, v[132:133]
	global_load_lds_dwordx4 v[216:217], off
	s_add_i32 m0, s24, 0x2000
	s_nop 0
	global_load_lds_dwordx4 v130, s[64:65]
	v_lshl_add_u64 v[216:217], s[22:23], 0, v[134:135]
	s_mov_b32 m0, s38
	s_nop 0
	global_load_lds_dwordx4 v[216:217], off
	s_mov_b32 m0, s39
	s_nop 0
	global_load_lds_dwordx4 v[218:219], off
	s_cmp_lg_u32 s100, 0
	s_cbranch_scc1 .Lcw_g6_p2
	s_waitcnt vmcnt(8)
.Lcw_g6_c2:
	s_waitcnt lgkmcnt(0)
	s_setprio 1
	s_barrier
	v_mfma_f32_16x16x32_bf16 v[62:65], v[140:143], v[180:183], v[62:65]
	v_mfma_f32_16x16x32_bf16 v[58:61], v[148:151], v[180:183], v[58:61]
	v_mfma_f32_16x16x32_bf16 v[46:49], v[140:143], v[188:191], v[46:49]
	v_mfma_f32_16x16x32_bf16 v[42:45], v[148:151], v[188:191], v[42:45]
	v_mfma_f32_16x16x32_bf16 v[30:33], v[140:143], v[196:199], v[30:33]
	v_mfma_f32_16x16x32_bf16 v[26:29], v[148:151], v[196:199], v[26:29]
	v_mfma_f32_16x16x32_bf16 v[14:17], v[140:143], v[204:207], v[14:17]
	v_mfma_f32_16x16x32_bf16 v[10:13], v[148:151], v[204:207], v[10:13]
	v_mfma_f32_16x16x32_bf16 v[62:65], v[144:147], v[184:187], v[62:65]
	v_mfma_f32_16x16x32_bf16 v[58:61], v[160:163], v[184:187], v[58:61]
	v_mfma_f32_16x16x32_bf16 v[46:49], v[144:147], v[192:195], v[46:49]
	v_mfma_f32_16x16x32_bf16 v[42:45], v[160:163], v[192:195], v[42:45]
	v_mfma_f32_16x16x32_bf16 v[30:33], v[144:147], v[200:203], v[30:33]
	v_mfma_f32_16x16x32_bf16 v[26:29], v[160:163], v[200:203], v[26:29]
	v_mfma_f32_16x16x32_bf16 v[14:17], v[144:147], v[208:211], v[14:17]
	v_mfma_f32_16x16x32_bf16 v[10:13], v[160:163], v[208:211], v[10:13]
	s_setprio 0
	s_setprio 1
	v_mfma_f32_16x16x32_bf16 v[54:57], v[164:167], v[180:183], v[54:57]
	v_mfma_f32_16x16x32_bf16 v[50:53], v[172:175], v[180:183], v[50:53]
	v_mfma_f32_16x16x32_bf16 v[38:41], v[164:167], v[188:191], v[38:41]
	v_mfma_f32_16x16x32_bf16 v[34:37], v[172:175], v[188:191], v[34:37]
	v_mfma_f32_16x16x32_bf16 v[22:25], v[164:167], v[196:199], v[22:25]
	v_mfma_f32_16x16x32_bf16 v[18:21], v[172:175], v[196:199], v[18:21]
	v_mfma_f32_16x16x32_bf16 v[6:9], v[164:167], v[204:207], v[6:9]
	v_mfma_f32_16x16x32_bf16 v[2:5], v[172:175], v[204:207], v[2:5]
	v_mfma_f32_16x16x32_bf16 v[54:57], v[168:171], v[184:187], v[54:57]
	v_mfma_f32_16x16x32_bf16 v[50:53], v[176:179], v[184:187], v[50:53]
	v_mfma_f32_16x16x32_bf16 v[38:41], v[168:171], v[192:195], v[38:41]
	v_mfma_f32_16x16x32_bf16 v[34:37], v[176:179], v[192:195], v[34:37]
	v_mfma_f32_16x16x32_bf16 v[22:25], v[168:171], v[200:203], v[22:25]
	v_mfma_f32_16x16x32_bf16 v[18:21], v[176:179], v[200:203], v[18:21]
	v_mfma_f32_16x16x32_bf16 v[6:9], v[168:171], v[208:211], v[6:9]
	v_mfma_f32_16x16x32_bf16 v[2:5], v[176:179], v[208:211], v[2:5]
	s_barrier
	s_setprio 0
	s_add_i32 s24, 0, 0x18000
	s_add_i32 s63, 0, 0x1c000
	v_add_u32_e32 v160, s24, v153
	v_add_u32_e32 v176, s63, v153
	ds_read_b128 v[140:143], v160
	ds_read_b128 v[144:147], v160 offset:1024
	ds_read_b128 v[148:151], v160 offset:2048
	ds_read_b128 v[160:163], v160 offset:3072
	ds_read_b128 v[164:167], v176
	ds_read_b128 v[168:171], v176 offset:1024
	ds_read_b128 v[172:175], v176 offset:2048
	ds_read_b128 v[176:179], v176 offset:3072
	s_add_u32 s22, s22, 0x80000
	s_addc_u32 s23, s23, 0
	s_mov_b32 m0, s48
	ds_read_b128 v[180:183], v159 offset:32768
	ds_read_b128 v[184:187], v159 offset:33792
	ds_read_b128 v[188:191], v159 offset:34816
	ds_read_b128 v[192:195], v159 offset:35840
	ds_read_b128 v[196:199], v159 offset:36864
	ds_read_b128 v[200:203], v159 offset:37888
	ds_read_b128 v[204:207], v159 offset:38912
	ds_read_b128 v[208:211], v159 offset:39936
	global_load_lds_dwordx4 v134, s[22:23]
	s_mov_b32 m0, s49
	s_nop 0
	global_load_lds_dwordx4 v132, s[22:23]
	s_waitcnt vmcnt(8)
	s_waitcnt lgkmcnt(0)
	s_setprio 1
	s_barrier
	v_mfma_f32_16x16x32_bf16 v[126:129], v[140:143], v[180:183], v[126:129]
	v_mfma_f32_16x16x32_bf16 v[122:125], v[148:151], v[180:183], v[122:125]
	v_mfma_f32_16x16x32_bf16 v[110:113], v[140:143], v[188:191], v[110:113]
	v_mfma_f32_16x16x32_bf16 v[106:109], v[148:151], v[188:191], v[106:109]
	v_mfma_f32_16x16x32_bf16 v[94:97], v[140:143], v[196:199], v[94:97]
	v_mfma_f32_16x16x32_bf16 v[90:93], v[148:151], v[196:199], v[90:93]
	v_mfma_f32_16x16x32_bf16 v[78:81], v[140:143], v[204:207], v[78:81]
	v_mfma_f32_16x16x32_bf16 v[74:77], v[148:151], v[204:207], v[74:77]
	v_mfma_f32_16x16x32_bf16 v[126:129], v[144:147], v[184:187], v[126:129]
	v_mfma_f32_16x16x32_bf16 v[122:125], v[160:163], v[184:187], v[122:125]
	v_mfma_f32_16x16x32_bf16 v[110:113], v[144:147], v[192:195], v[110:113]
	v_mfma_f32_16x16x32_bf16 v[106:109], v[160:163], v[192:195], v[106:109]
	v_mfma_f32_16x16x32_bf16 v[94:97], v[144:147], v[200:203], v[94:97]
	v_mfma_f32_16x16x32_bf16 v[90:93], v[160:163], v[200:203], v[90:93]
	v_mfma_f32_16x16x32_bf16 v[78:81], v[144:147], v[208:211], v[78:81]
	v_mfma_f32_16x16x32_bf16 v[74:77], v[160:163], v[208:211], v[74:77]
	s_setprio 0
	s_setprio 1
	v_mfma_f32_16x16x32_bf16 v[118:121], v[164:167], v[180:183], v[118:121]
	v_mfma_f32_16x16x32_bf16 v[114:117], v[172:175], v[180:183], v[114:117]
	v_mfma_f32_16x16x32_bf16 v[102:105], v[164:167], v[188:191], v[102:105]
	v_mfma_f32_16x16x32_bf16 v[98:101], v[172:175], v[188:191], v[98:101]
	v_mfma_f32_16x16x32_bf16 v[86:89], v[164:167], v[196:199], v[86:89]
	v_mfma_f32_16x16x32_bf16 v[82:85], v[172:175], v[196:199], v[82:85]
	v_mfma_f32_16x16x32_bf16 v[70:73], v[164:167], v[204:207], v[70:73]
	v_mfma_f32_16x16x32_bf16 v[66:69], v[172:175], v[204:207], v[66:69]
	v_mfma_f32_16x16x32_bf16 v[118:121], v[168:171], v[184:187], v[118:121]
	v_mfma_f32_16x16x32_bf16 v[114:117], v[176:179], v[184:187], v[114:117]
	v_mfma_f32_16x16x32_bf16 v[102:105], v[168:171], v[192:195], v[102:105]
	v_mfma_f32_16x16x32_bf16 v[98:101], v[176:179], v[192:195], v[98:101]
	v_mfma_f32_16x16x32_bf16 v[86:89], v[168:171], v[200:203], v[86:89]
	v_mfma_f32_16x16x32_bf16 v[82:85], v[176:179], v[200:203], v[82:85]
	v_mfma_f32_16x16x32_bf16 v[70:73], v[168:171], v[208:211], v[70:73]
	v_mfma_f32_16x16x32_bf16 v[66:69], v[176:179], v[208:211], v[66:69]
	s_barrier
	s_setprio 0
	s_add_i32 s22, s24, s29
	v_lshl_add_u64 v[212:213], v[212:213], 0, s[34:35]
	s_mov_b32 m0, s22
	ds_read_b128 v[180:183], v159 offset:49152
	ds_read_b128 v[184:187], v159 offset:50176
	ds_read_b128 v[188:191], v159 offset:51200
	ds_read_b128 v[192:195], v159 offset:52224
	ds_read_b128 v[196:199], v159 offset:53248
	ds_read_b128 v[200:203], v159 offset:54272
	ds_read_b128 v[204:207], v159 offset:55296
	ds_read_b128 v[208:211], v159 offset:56320
	global_load_lds_dwordx4 v[212:213], off
	s_add_i32 m0, s22, 0x2000
	s_add_u32 s22, s26, 0x80080
	v_lshl_add_u64 v[212:213], v[214:215], 0, s[34:35]
	s_addc_u32 s23, s27, 0
	s_add_i32 s24, s63, s29
	global_load_lds_dwordx4 v[212:213], off
	v_lshl_add_u64 v[212:213], s[22:23], 0, v[0:1]
	s_mov_b32 m0, s24
	s_nop 0
	global_load_lds_dwordx4 v[212:213], off
	s_add_i32 m0, s24, 0x2000
	s_nop 0
	global_load_lds_dwordx4 v130, s[22:23]
	v_lshl_add_u64 v[212:213], v[216:217], 0, s[34:35]
	s_mov_b32 m0, s51
	s_nop 0
	global_load_lds_dwordx4 v[212:213], off
	v_lshl_add_u64 v[212:213], v[218:219], 0, s[34:35]
	s_mov_b32 m0, s56
	s_nop 0
	global_load_lds_dwordx4 v[212:213], off
	s_waitcnt vmcnt(8)
	s_waitcnt lgkmcnt(0)
	s_setprio 1
	s_barrier
	v_mfma_f32_16x16x32_bf16 v[62:65], v[140:143], v[180:183], v[62:65]
	v_mfma_f32_16x16x32_bf16 v[58:61], v[148:151], v[180:183], v[58:61]
	v_mfma_f32_16x16x32_bf16 v[46:49], v[140:143], v[188:191], v[46:49]
	v_mfma_f32_16x16x32_bf16 v[42:45], v[148:151], v[188:191], v[42:45]
	v_mfma_f32_16x16x32_bf16 v[30:33], v[140:143], v[196:199], v[30:33]
	v_mfma_f32_16x16x32_bf16 v[26:29], v[148:151], v[196:199], v[26:29]
	v_mfma_f32_16x16x32_bf16 v[14:17], v[140:143], v[204:207], v[14:17]
	v_mfma_f32_16x16x32_bf16 v[10:13], v[148:151], v[204:207], v[10:13]
	v_mfma_f32_16x16x32_bf16 v[62:65], v[144:147], v[184:187], v[62:65]
	v_mfma_f32_16x16x32_bf16 v[58:61], v[160:163], v[184:187], v[58:61]
	v_mfma_f32_16x16x32_bf16 v[46:49], v[144:147], v[192:195], v[46:49]
	v_mfma_f32_16x16x32_bf16 v[42:45], v[160:163], v[192:195], v[42:45]
	v_mfma_f32_16x16x32_bf16 v[30:33], v[144:147], v[200:203], v[30:33]
	v_mfma_f32_16x16x32_bf16 v[26:29], v[160:163], v[200:203], v[26:29]
	v_mfma_f32_16x16x32_bf16 v[14:17], v[144:147], v[208:211], v[14:17]
	v_mfma_f32_16x16x32_bf16 v[10:13], v[160:163], v[208:211], v[10:13]
	s_setprio 0
	s_setprio 1
	v_mfma_f32_16x16x32_bf16 v[54:57], v[164:167], v[180:183], v[54:57]
	v_mfma_f32_16x16x32_bf16 v[50:53], v[172:175], v[180:183], v[50:53]
	v_mfma_f32_16x16x32_bf16 v[38:41], v[164:167], v[188:191], v[38:41]
	v_mfma_f32_16x16x32_bf16 v[34:37], v[172:175], v[188:191], v[34:37]
	v_mfma_f32_16x16x32_bf16 v[22:25], v[164:167], v[196:199], v[22:25]
	v_mfma_f32_16x16x32_bf16 v[18:21], v[172:175], v[196:199], v[18:21]
	v_mfma_f32_16x16x32_bf16 v[6:9], v[164:167], v[204:207], v[6:9]
	v_mfma_f32_16x16x32_bf16 v[2:5], v[172:175], v[204:207], v[2:5]
	v_mfma_f32_16x16x32_bf16 v[54:57], v[168:171], v[184:187], v[54:57]
	v_mfma_f32_16x16x32_bf16 v[50:53], v[176:179], v[184:187], v[50:53]
	v_mfma_f32_16x16x32_bf16 v[38:41], v[168:171], v[192:195], v[38:41]
	v_mfma_f32_16x16x32_bf16 v[34:37], v[176:179], v[192:195], v[34:37]
	v_mfma_f32_16x16x32_bf16 v[22:25], v[168:171], v[200:203], v[22:25]
	v_mfma_f32_16x16x32_bf16 v[18:21], v[176:179], v[200:203], v[18:21]
	v_mfma_f32_16x16x32_bf16 v[6:9], v[168:171], v[208:211], v[6:9]
	v_mfma_f32_16x16x32_bf16 v[2:5], v[176:179], v[208:211], v[2:5]
	s_barrier
	s_setprio 0
	s_add_i32 s62, s62, 2
	s_add_u32 s20, s20, 0x100
	s_addc_u32 s21, s21, 0
	s_add_u32 s46, s46, 0x100
	s_addc_u32 s47, s47, 0
	s_cmp_gt_u32 s62, 29
	s_cbranch_scc0 .LBB0_774
	s_and_b64 vcc, exec, s[10:11]
	s_cbranch_vccz .LBB0_777
	s_barrier

.LBB0_882:
	s_add_u32 s22, s46, 0xffe00080
	s_addc_u32 s23, s47, -1
	s_add_i32 s24, 0, 0x10000
	s_cmpk_eq_i32 s39, 0x7c
	s_cselect_b32 s23, s13, s23
	s_cselect_b32 s22, s19, s22
	s_cselect_b32 s27, s11, s37
	s_cselect_b32 s26, s21, s36
	s_add_i32 s64, 0, 0x14000
	v_add_u32_e32 v142, s24, v209
	v_add_u32_e32 v168, s64, v209
	ds_read_b128 v[130:133], v142
	ds_read_b128 v[134:137], v142 offset:1024
	ds_read_b128 v[138:141], v142 offset:2048
	ds_read_b128 v[142:145], v142 offset:3072
	ds_read_b128 v[146:149], v168
	ds_read_b128 v[150:153], v168 offset:1024
	ds_read_b128 v[154:157], v168 offset:2048
	ds_read_b128 v[168:171], v168 offset:3072
	s_add_i32 m0, s60, 0xc000
	ds_read_b128 v[172:175], v224
	ds_read_b128 v[176:179], v224 offset:1024
	ds_read_b128 v[180:183], v224 offset:2048
	ds_read_b128 v[184:187], v224 offset:3072
	ds_read_b128 v[188:191], v224 offset:4096
	ds_read_b128 v[192:195], v224 offset:5120
	ds_read_b128 v[196:199], v224 offset:6144
	ds_read_b128 v[200:203], v224 offset:7168
	global_load_lds_dwordx4 v164, s[46:47]
	s_add_i32 m0, s60, 0xe000
	s_nop 0
	global_load_lds_dwordx4 v166, s[46:47]
	s_waitcnt vmcnt(8)
	s_waitcnt lgkmcnt(0)
	s_setprio 1
	s_barrier
	v_mfma_f32_16x16x32_bf16 v[126:129], v[130:133], v[172:175], v[126:129]
	v_mfma_f32_16x16x32_bf16 v[122:125], v[138:141], v[172:175], v[122:125]
	v_mfma_f32_16x16x32_bf16 v[110:113], v[130:133], v[180:183], v[110:113]
	v_mfma_f32_16x16x32_bf16 v[106:109], v[138:141], v[180:183], v[106:109]
	v_mfma_f32_16x16x32_bf16 v[94:97], v[130:133], v[188:191], v[94:97]
	v_mfma_f32_16x16x32_bf16 v[90:93], v[138:141], v[188:191], v[90:93]
	v_mfma_f32_16x16x32_bf16 v[78:81], v[130:133], v[196:199], v[78:81]
	v_mfma_f32_16x16x32_bf16 v[74:77], v[138:141], v[196:199], v[74:77]
	v_mfma_f32_16x16x32_bf16 v[126:129], v[134:137], v[176:179], v[126:129]
	v_mfma_f32_16x16x32_bf16 v[122:125], v[142:145], v[176:179], v[122:125]
	v_mfma_f32_16x16x32_bf16 v[110:113], v[134:137], v[184:187], v[110:113]
	v_mfma_f32_16x16x32_bf16 v[106:109], v[142:145], v[184:187], v[106:109]
	v_mfma_f32_16x16x32_bf16 v[94:97], v[134:137], v[192:195], v[94:97]
	v_mfma_f32_16x16x32_bf16 v[90:93], v[142:145], v[192:195], v[90:93]
	v_mfma_f32_16x16x32_bf16 v[78:81], v[134:137], v[200:203], v[78:81]
	v_mfma_f32_16x16x32_bf16 v[74:77], v[142:145], v[200:203], v[74:77]
	s_setprio 0
	s_setprio 1
	v_mfma_f32_16x16x32_bf16 v[118:121], v[146:149], v[172:175], v[118:121]
	v_mfma_f32_16x16x32_bf16 v[114:117], v[154:157], v[172:175], v[114:117]
	v_mfma_f32_16x16x32_bf16 v[102:105], v[146:149], v[180:183], v[102:105]
	v_mfma_f32_16x16x32_bf16 v[98:101], v[154:157], v[180:183], v[98:101]
	v_mfma_f32_16x16x32_bf16 v[86:89], v[146:149], v[188:191], v[86:89]
	v_mfma_f32_16x16x32_bf16 v[82:85], v[154:157], v[188:191], v[82:85]
	v_mfma_f32_16x16x32_bf16 v[70:73], v[146:149], v[196:199], v[70:73]
	v_mfma_f32_16x16x32_bf16 v[66:69], v[154:157], v[196:199], v[66:69]
	v_mfma_f32_16x16x32_bf16 v[118:121], v[150:153], v[176:179], v[118:121]
	v_mfma_f32_16x16x32_bf16 v[114:117], v[168:171], v[176:179], v[114:117]
	v_mfma_f32_16x16x32_bf16 v[102:105], v[150:153], v[184:187], v[102:105]
	v_mfma_f32_16x16x32_bf16 v[98:101], v[168:171], v[184:187], v[98:101]
	v_mfma_f32_16x16x32_bf16 v[86:89], v[150:153], v[192:195], v[86:89]
	v_mfma_f32_16x16x32_bf16 v[82:85], v[168:171], v[192:195], v[82:85]
	v_mfma_f32_16x16x32_bf16 v[70:73], v[150:153], v[200:203], v[70:73]
	v_mfma_f32_16x16x32_bf16 v[66:69], v[168:171], v[200:203], v[66:69]
	s_barrier
	s_setprio 0
	s_add_i32 s24, s24, s57
	v_lshl_add_u64 v[204:205], s[26:27], 0, v[0:1]
	s_mov_b32 m0, s24
	ds_read_b128 v[172:175], v224 offset:16384
	ds_read_b128 v[176:179], v224 offset:17408
	ds_read_b128 v[180:183], v224 offset:18432
	ds_read_b128 v[184:187], v224 offset:19456
	ds_read_b128 v[188:191], v224 offset:20480
	ds_read_b128 v[192:195], v224 offset:21504
	ds_read_b128 v[196:199], v224 offset:22528
	ds_read_b128 v[200:203], v224 offset:23552
	global_load_lds_dwordx4 v[204:205], off
	s_add_i32 m0, s24, 0x2000
	s_add_u32 s62, s26, 0x200000
	v_lshl_add_u64 v[214:215], s[26:27], 0, v[162:163]
	s_addc_u32 s63, s27, 0
	s_add_i32 s24, s64, s57
	global_load_lds_dwordx4 v[214:215], off
	v_lshl_add_u64 v[230:231], s[62:63], 0, v[0:1]
	s_mov_b32 m0, s24
	v_lshl_add_u64 v[232:233], s[22:23], 0, v[160:161]
	global_load_lds_dwordx4 v[230:231], off
	s_add_i32 m0, s24, 0x2000
	s_nop 0
	global_load_lds_dwordx4 v162, s[62:63]
	v_lshl_add_u64 v[230:231], s[22:23], 0, v[158:159]
	s_mov_b32 m0, s60
	s_nop 0
	global_load_lds_dwordx4 v[230:231], off
	s_mov_b32 m0, s61
	s_nop 0
	global_load_lds_dwordx4 v[232:233], off
	s_waitcnt vmcnt(8)
	s_waitcnt lgkmcnt(0)
	s_setprio 1
	s_barrier
	v_mfma_f32_16x16x32_bf16 v[62:65], v[130:133], v[172:175], v[62:65]
	v_mfma_f32_16x16x32_bf16 v[58:61], v[138:141], v[172:175], v[58:61]
	v_mfma_f32_16x16x32_bf16 v[46:49], v[130:133], v[180:183], v[46:49]
	v_mfma_f32_16x16x32_bf16 v[42:45], v[138:141], v[180:183], v[42:45]
	v_mfma_f32_16x16x32_bf16 v[30:33], v[130:133], v[188:191], v[30:33]
	v_mfma_f32_16x16x32_bf16 v[26:29], v[138:141], v[188:191], v[26:29]
	v_mfma_f32_16x16x32_bf16 v[14:17], v[130:133], v[196:199], v[14:17]
	v_mfma_f32_16x16x32_bf16 v[10:13], v[138:141], v[196:199], v[10:13]
	v_mfma_f32_16x16x32_bf16 v[62:65], v[134:137], v[176:179], v[62:65]
	v_mfma_f32_16x16x32_bf16 v[58:61], v[142:145], v[176:179], v[58:61]
	v_mfma_f32_16x16x32_bf16 v[46:49], v[134:137], v[184:187], v[46:49]
	v_mfma_f32_16x16x32_bf16 v[42:45], v[142:145], v[184:187], v[42:45]
	v_mfma_f32_16x16x32_bf16 v[30:33], v[134:137], v[192:195], v[30:33]
	v_mfma_f32_16x16x32_bf16 v[26:29], v[142:145], v[192:195], v[26:29]
	v_mfma_f32_16x16x32_bf16 v[14:17], v[134:137], v[200:203], v[14:17]
	v_mfma_f32_16x16x32_bf16 v[10:13], v[142:145], v[200:203], v[10:13]
	s_setprio 0
	s_setprio 1
	v_mfma_f32_16x16x32_bf16 v[54:57], v[146:149], v[172:175], v[54:57]
	v_mfma_f32_16x16x32_bf16 v[50:53], v[154:157], v[172:175], v[50:53]
	v_mfma_f32_16x16x32_bf16 v[38:41], v[146:149], v[180:183], v[38:41]
	v_mfma_f32_16x16x32_bf16 v[34:37], v[154:157], v[180:183], v[34:37]
	v_mfma_f32_16x16x32_bf16 v[22:25], v[146:149], v[188:191], v[22:25]
	v_mfma_f32_16x16x32_bf16 v[18:21], v[154:157], v[188:191], v[18:21]
	v_mfma_f32_16x16x32_bf16 v[6:9], v[146:149], v[196:199], v[6:9]
	v_mfma_f32_16x16x32_bf16 v[2:5], v[154:157], v[196:199], v[2:5]
	v_mfma_f32_16x16x32_bf16 v[54:57], v[150:153], v[176:179], v[54:57]
	v_mfma_f32_16x16x32_bf16 v[50:53], v[168:171], v[176:179], v[50:53]
	v_mfma_f32_16x16x32_bf16 v[38:41], v[150:153], v[184:187], v[38:41]
	v_mfma_f32_16x16x32_bf16 v[34:37], v[168:171], v[184:187], v[34:37]
	v_mfma_f32_16x16x32_bf16 v[22:25], v[150:153], v[192:195], v[22:25]
	v_mfma_f32_16x16x32_bf16 v[18:21], v[168:171], v[192:195], v[18:21]
	v_mfma_f32_16x16x32_bf16 v[6:9], v[150:153], v[200:203], v[6:9]
	v_mfma_f32_16x16x32_bf16 v[2:5], v[168:171], v[200:203], v[2:5]
	s_barrier
	s_setprio 0
	s_add_i32 s24, 0, 0x18000
	s_add_i32 s62, 0, 0x1c000
	v_add_u32_e32 v142, s24, v209
	v_add_u32_e32 v168, s62, v209
	ds_read_b128 v[130:133], v142
	ds_read_b128 v[134:137], v142 offset:1024
	ds_read_b128 v[138:141], v142 offset:2048
	ds_read_b128 v[142:145], v142 offset:3072
	ds_read_b128 v[146:149], v168
	ds_read_b128 v[150:153], v168 offset:1024
	ds_read_b128 v[154:157], v168 offset:2048
	ds_read_b128 v[168:171], v168 offset:3072
	s_add_u32 s22, s22, 0x200000
	s_addc_u32 s23, s23, 0
	s_mov_b32 m0, s76
	ds_read_b128 v[172:175], v224 offset:32768
	ds_read_b128 v[176:179], v224 offset:33792
	ds_read_b128 v[180:183], v224 offset:34816
	ds_read_b128 v[184:187], v224 offset:35840
	ds_read_b128 v[188:191], v224 offset:36864
	ds_read_b128 v[192:195], v224 offset:37888
	ds_read_b128 v[196:199], v224 offset:38912
	ds_read_b128 v[200:203], v224 offset:39936
	global_load_lds_dwordx4 v158, s[22:23]
	s_mov_b32 m0, s77
	s_nop 0
	global_load_lds_dwordx4 v160, s[22:23]
	s_waitcnt vmcnt(8)
	s_waitcnt lgkmcnt(0)
	s_setprio 1
	s_barrier
	v_mfma_f32_16x16x32_bf16 v[126:129], v[130:133], v[172:175], v[126:129]
	v_mfma_f32_16x16x32_bf16 v[122:125], v[138:141], v[172:175], v[122:125]
	v_mfma_f32_16x16x32_bf16 v[110:113], v[130:133], v[180:183], v[110:113]
	v_mfma_f32_16x16x32_bf16 v[106:109], v[138:141], v[180:183], v[106:109]
	v_mfma_f32_16x16x32_bf16 v[94:97], v[130:133], v[188:191], v[94:97]
	v_mfma_f32_16x16x32_bf16 v[90:93], v[138:141], v[188:191], v[90:93]
	v_mfma_f32_16x16x32_bf16 v[78:81], v[130:133], v[196:199], v[78:81]
	v_mfma_f32_16x16x32_bf16 v[74:77], v[138:141], v[196:199], v[74:77]
	v_mfma_f32_16x16x32_bf16 v[126:129], v[134:137], v[176:179], v[126:129]
	v_mfma_f32_16x16x32_bf16 v[122:125], v[142:145], v[176:179], v[122:125]
	v_mfma_f32_16x16x32_bf16 v[110:113], v[134:137], v[184:187], v[110:113]
	v_mfma_f32_16x16x32_bf16 v[106:109], v[142:145], v[184:187], v[106:109]
	v_mfma_f32_16x16x32_bf16 v[94:97], v[134:137], v[192:195], v[94:97]
	v_mfma_f32_16x16x32_bf16 v[90:93], v[142:145], v[192:195], v[90:93]
	v_mfma_f32_16x16x32_bf16 v[78:81], v[134:137], v[200:203], v[78:81]
	v_mfma_f32_16x16x32_bf16 v[74:77], v[142:145], v[200:203], v[74:77]
	s_setprio 0
	s_setprio 1
	v_mfma_f32_16x16x32_bf16 v[118:121], v[146:149], v[172:175], v[118:121]
	v_mfma_f32_16x16x32_bf16 v[114:117], v[154:157], v[172:175], v[114:117]
	v_mfma_f32_16x16x32_bf16 v[102:105], v[146:149], v[180:183], v[102:105]
	v_mfma_f32_16x16x32_bf16 v[98:101], v[154:157], v[180:183], v[98:101]
	v_mfma_f32_16x16x32_bf16 v[86:89], v[146:149], v[188:191], v[86:89]
	v_mfma_f32_16x16x32_bf16 v[82:85], v[154:157], v[188:191], v[82:85]
	v_mfma_f32_16x16x32_bf16 v[70:73], v[146:149], v[196:199], v[70:73]
	v_mfma_f32_16x16x32_bf16 v[66:69], v[154:157], v[196:199], v[66:69]
	v_mfma_f32_16x16x32_bf16 v[118:121], v[150:153], v[176:179], v[118:121]
	v_mfma_f32_16x16x32_bf16 v[114:117], v[168:171], v[176:179], v[114:117]
	v_mfma_f32_16x16x32_bf16 v[102:105], v[150:153], v[184:187], v[102:105]
	v_mfma_f32_16x16x32_bf16 v[98:101], v[168:171], v[184:187], v[98:101]
	v_mfma_f32_16x16x32_bf16 v[86:89], v[150:153], v[192:195], v[86:89]
	v_mfma_f32_16x16x32_bf16 v[82:85], v[168:171], v[192:195], v[82:85]
	v_mfma_f32_16x16x32_bf16 v[70:73], v[150:153], v[200:203], v[70:73]
	v_mfma_f32_16x16x32_bf16 v[66:69], v[168:171], v[200:203], v[66:69]
	s_barrier
	s_setprio 0
	s_add_i32 s22, s24, s57
	v_lshl_add_u64 v[204:205], v[204:205], 0, s[34:35]
	s_mov_b32 m0, s22
	ds_read_b128 v[172:175], v224 offset:49152
	ds_read_b128 v[176:179], v224 offset:50176
	ds_read_b128 v[180:183], v224 offset:51200
	ds_read_b128 v[184:187], v224 offset:52224
	ds_read_b128 v[188:191], v224 offset:53248
	ds_read_b128 v[192:195], v224 offset:54272
	ds_read_b128 v[196:199], v224 offset:55296
	ds_read_b128 v[200:203], v224 offset:56320
	global_load_lds_dwordx4 v[204:205], off
	s_add_i32 m0, s22, 0x2000
	s_add_u32 s22, s26, 0x200080
	v_lshl_add_u64 v[204:205], v[214:215], 0, s[34:35]
	s_addc_u32 s23, s27, 0
	s_add_i32 s24, s62, s57
	global_load_lds_dwordx4 v[204:205], off
	v_lshl_add_u64 v[204:205], s[22:23], 0, v[0:1]
	s_mov_b32 m0, s24
	s_nop 0
	global_load_lds_dwordx4 v[204:205], off
	s_add_i32 m0, s24, 0x2000
	s_nop 0
	global_load_lds_dwordx4 v162, s[22:23]
	v_lshl_add_u64 v[204:205], v[230:231], 0, s[34:35]
	s_mov_b32 m0, s81
	s_nop 0
	global_load_lds_dwordx4 v[204:205], off
	v_lshl_add_u64 v[204:205], v[232:233], 0, s[34:35]
	s_mov_b32 m0, s82
	s_nop 0
	global_load_lds_dwordx4 v[204:205], off
	s_waitcnt vmcnt(8)
	s_waitcnt lgkmcnt(0)
	s_setprio 1
	s_barrier
	v_mfma_f32_16x16x32_bf16 v[62:65], v[130:133], v[172:175], v[62:65]
	v_mfma_f32_16x16x32_bf16 v[58:61], v[138:141], v[172:175], v[58:61]
	v_mfma_f32_16x16x32_bf16 v[46:49], v[130:133], v[180:183], v[46:49]
	v_mfma_f32_16x16x32_bf16 v[42:45], v[138:141], v[180:183], v[42:45]
	v_mfma_f32_16x16x32_bf16 v[30:33], v[130:133], v[188:191], v[30:33]
	v_mfma_f32_16x16x32_bf16 v[26:29], v[138:141], v[188:191], v[26:29]
	v_mfma_f32_16x16x32_bf16 v[14:17], v[130:133], v[196:199], v[14:17]
	v_mfma_f32_16x16x32_bf16 v[10:13], v[138:141], v[196:199], v[10:13]
	v_mfma_f32_16x16x32_bf16 v[62:65], v[134:137], v[176:179], v[62:65]
	v_mfma_f32_16x16x32_bf16 v[58:61], v[142:145], v[176:179], v[58:61]
	v_mfma_f32_16x16x32_bf16 v[46:49], v[134:137], v[184:187], v[46:49]
	v_mfma_f32_16x16x32_bf16 v[42:45], v[142:145], v[184:187], v[42:45]
	v_mfma_f32_16x16x32_bf16 v[30:33], v[134:137], v[192:195], v[30:33]
	v_mfma_f32_16x16x32_bf16 v[26:29], v[142:145], v[192:195], v[26:29]
	v_mfma_f32_16x16x32_bf16 v[14:17], v[134:137], v[200:203], v[14:17]
	v_mfma_f32_16x16x32_bf16 v[10:13], v[142:145], v[200:203], v[10:13]
	s_setprio 0
	s_setprio 1
	v_mfma_f32_16x16x32_bf16 v[54:57], v[146:149], v[172:175], v[54:57]
	v_mfma_f32_16x16x32_bf16 v[50:53], v[154:157], v[172:175], v[50:53]
	v_mfma_f32_16x16x32_bf16 v[38:41], v[146:149], v[180:183], v[38:41]
	v_mfma_f32_16x16x32_bf16 v[34:37], v[154:157], v[180:183], v[34:37]
	v_mfma_f32_16x16x32_bf16 v[22:25], v[146:149], v[188:191], v[22:25]
	v_mfma_f32_16x16x32_bf16 v[18:21], v[154:157], v[188:191], v[18:21]
	v_mfma_f32_16x16x32_bf16 v[6:9], v[146:149], v[196:199], v[6:9]
	v_mfma_f32_16x16x32_bf16 v[2:5], v[154:157], v[196:199], v[2:5]
	v_mfma_f32_16x16x32_bf16 v[54:57], v[150:153], v[176:179], v[54:57]
	v_mfma_f32_16x16x32_bf16 v[50:53], v[168:171], v[176:179], v[50:53]
	v_mfma_f32_16x16x32_bf16 v[38:41], v[150:153], v[184:187], v[38:41]
	v_mfma_f32_16x16x32_bf16 v[34:37], v[168:171], v[184:187], v[34:37]
	v_mfma_f32_16x16x32_bf16 v[22:25], v[150:153], v[192:195], v[22:25]
	v_mfma_f32_16x16x32_bf16 v[18:21], v[168:171], v[192:195], v[18:21]
	v_mfma_f32_16x16x32_bf16 v[6:9], v[150:153], v[200:203], v[6:9]
	v_mfma_f32_16x16x32_bf16 v[2:5], v[168:171], v[200:203], v[2:5]
	s_barrier
	s_setprio 0
	s_add_i32 s39, s39, 2
	s_add_u32 s46, s46, 0x100
	s_addc_u32 s47, s47, 0
	s_add_u32 s36, s36, 0x100
	s_addc_u32 s37, s37, 0
	s_cmpk_gt_u32 s39, 0x7d
	s_cbranch_scc0 .LBB0_882
	s_and_b64 vcc, exec, s[8:9]
	s_cbranch_vccz .LBB0_885
	s_barrier

.LBB0_1004:
	s_add_u32 s22, s46, 0xffe00080
	s_addc_u32 s23, s47, -1
	s_add_i32 s24, 0, 0x10000
	s_cmpk_eq_i32 s48, 0x7c
	s_cselect_b32 s23, s3, s23
	s_cselect_b32 s22, s15, s22
	s_cselect_b32 s27, s13, s37
	s_cselect_b32 s26, s21, s36
	s_add_i32 s49, 0, 0x14000
	v_add_u32_e32 v142, s24, v177
	v_add_u32_e32 v168, s49, v177
	ds_read_b128 v[130:133], v142
	ds_read_b128 v[134:137], v142 offset:1024
	ds_read_b128 v[138:141], v142 offset:2048
	ds_read_b128 v[142:145], v142 offset:3072
	ds_read_b128 v[146:149], v168
	ds_read_b128 v[150:153], v168 offset:1024
	ds_read_b128 v[164:167], v168 offset:2048
	ds_read_b128 v[168:171], v168 offset:3072
	s_add_i32 m0, s60, 0xc000
	ds_read_b128 v[172:175], v181
	ds_read_b128 v[184:187], v181 offset:1024
	ds_read_b128 v[188:191], v181 offset:2048
	ds_read_b128 v[192:195], v181 offset:3072
	ds_read_b128 v[196:199], v181 offset:4096
	ds_read_b128 v[200:203], v181 offset:5120
	ds_read_b128 v[204:207], v181 offset:6144
	ds_read_b128 v[208:211], v181 offset:7168
	global_load_lds_dwordx4 v160, s[46:47]
	s_add_i32 m0, s60, 0xe000
	s_nop 0
	global_load_lds_dwordx4 v162, s[46:47]
	s_waitcnt vmcnt(8)
	s_waitcnt lgkmcnt(0)
	s_setprio 1
	s_barrier
	v_mfma_f32_16x16x32_bf16 v[126:129], v[130:133], v[172:175], v[126:129]
	v_mfma_f32_16x16x32_bf16 v[122:125], v[138:141], v[172:175], v[122:125]
	v_mfma_f32_16x16x32_bf16 v[110:113], v[130:133], v[188:191], v[110:113]
	v_mfma_f32_16x16x32_bf16 v[106:109], v[138:141], v[188:191], v[106:109]
	v_mfma_f32_16x16x32_bf16 v[94:97], v[130:133], v[196:199], v[94:97]
	v_mfma_f32_16x16x32_bf16 v[90:93], v[138:141], v[196:199], v[90:93]
	v_mfma_f32_16x16x32_bf16 v[78:81], v[130:133], v[204:207], v[78:81]
	v_mfma_f32_16x16x32_bf16 v[74:77], v[138:141], v[204:207], v[74:77]
	v_mfma_f32_16x16x32_bf16 v[126:129], v[134:137], v[184:187], v[126:129]
	v_mfma_f32_16x16x32_bf16 v[122:125], v[142:145], v[184:187], v[122:125]
	v_mfma_f32_16x16x32_bf16 v[110:113], v[134:137], v[192:195], v[110:113]
	v_mfma_f32_16x16x32_bf16 v[106:109], v[142:145], v[192:195], v[106:109]
	v_mfma_f32_16x16x32_bf16 v[94:97], v[134:137], v[200:203], v[94:97]
	v_mfma_f32_16x16x32_bf16 v[90:93], v[142:145], v[200:203], v[90:93]
	v_mfma_f32_16x16x32_bf16 v[78:81], v[134:137], v[208:211], v[78:81]
	v_mfma_f32_16x16x32_bf16 v[74:77], v[142:145], v[208:211], v[74:77]
	s_setprio 0
	s_setprio 1
	v_mfma_f32_16x16x32_bf16 v[118:121], v[146:149], v[172:175], v[118:121]
	v_mfma_f32_16x16x32_bf16 v[114:117], v[164:167], v[172:175], v[114:117]
	v_mfma_f32_16x16x32_bf16 v[102:105], v[146:149], v[188:191], v[102:105]
	v_mfma_f32_16x16x32_bf16 v[98:101], v[164:167], v[188:191], v[98:101]
	v_mfma_f32_16x16x32_bf16 v[86:89], v[146:149], v[196:199], v[86:89]
	v_mfma_f32_16x16x32_bf16 v[82:85], v[164:167], v[196:199], v[82:85]
	v_mfma_f32_16x16x32_bf16 v[70:73], v[146:149], v[204:207], v[70:73]
	v_mfma_f32_16x16x32_bf16 v[66:69], v[164:167], v[204:207], v[66:69]
	v_mfma_f32_16x16x32_bf16 v[118:121], v[150:153], v[184:187], v[118:121]
	v_mfma_f32_16x16x32_bf16 v[114:117], v[168:171], v[184:187], v[114:117]
	v_mfma_f32_16x16x32_bf16 v[102:105], v[150:153], v[192:195], v[102:105]
	v_mfma_f32_16x16x32_bf16 v[98:101], v[168:171], v[192:195], v[98:101]
	v_mfma_f32_16x16x32_bf16 v[86:89], v[150:153], v[200:203], v[86:89]
	v_mfma_f32_16x16x32_bf16 v[82:85], v[168:171], v[200:203], v[82:85]
	v_mfma_f32_16x16x32_bf16 v[70:73], v[150:153], v[208:211], v[70:73]
	v_mfma_f32_16x16x32_bf16 v[66:69], v[168:171], v[208:211], v[66:69]
	s_barrier
	s_setprio 0
	s_add_i32 s24, s24, s57
	v_lshl_add_u64 v[212:213], s[26:27], 0, v[0:1]
	s_mov_b32 m0, s24
	ds_read_b128 v[172:175], v181 offset:16384
	ds_read_b128 v[184:187], v181 offset:17408
	ds_read_b128 v[188:191], v181 offset:18432
	ds_read_b128 v[192:195], v181 offset:19456
	ds_read_b128 v[196:199], v181 offset:20480
	ds_read_b128 v[200:203], v181 offset:21504
	ds_read_b128 v[204:207], v181 offset:22528
	ds_read_b128 v[208:211], v181 offset:23552
	global_load_lds_dwordx4 v[212:213], off
	s_add_i32 m0, s24, 0x2000
	s_add_u32 s50, s26, 0x200000
	v_lshl_add_u64 v[214:215], s[26:27], 0, v[158:159]
	s_addc_u32 s51, s27, 0
	s_add_i32 s24, s49, s57
	global_load_lds_dwordx4 v[214:215], off
	v_lshl_add_u64 v[216:217], s[50:51], 0, v[0:1]
	s_mov_b32 m0, s24
	v_lshl_add_u64 v[218:219], s[22:23], 0, v[156:157]
	global_load_lds_dwordx4 v[216:217], off
	s_add_i32 m0, s24, 0x2000
	s_nop 0
	global_load_lds_dwordx4 v158, s[50:51]
	v_lshl_add_u64 v[216:217], s[22:23], 0, v[154:155]
	s_mov_b32 m0, s60
	s_nop 0
	global_load_lds_dwordx4 v[216:217], off
	s_mov_b32 m0, s61
	s_nop 0
	global_load_lds_dwordx4 v[218:219], off
	s_waitcnt vmcnt(8)
	s_waitcnt lgkmcnt(0)
	s_setprio 1
	s_barrier
	v_mfma_f32_16x16x32_bf16 v[62:65], v[130:133], v[172:175], v[62:65]
	v_mfma_f32_16x16x32_bf16 v[58:61], v[138:141], v[172:175], v[58:61]
	v_mfma_f32_16x16x32_bf16 v[46:49], v[130:133], v[188:191], v[46:49]
	v_mfma_f32_16x16x32_bf16 v[42:45], v[138:141], v[188:191], v[42:45]
	v_mfma_f32_16x16x32_bf16 v[30:33], v[130:133], v[196:199], v[30:33]
	v_mfma_f32_16x16x32_bf16 v[26:29], v[138:141], v[196:199], v[26:29]
	v_mfma_f32_16x16x32_bf16 v[14:17], v[130:133], v[204:207], v[14:17]
	v_mfma_f32_16x16x32_bf16 v[10:13], v[138:141], v[204:207], v[10:13]
	v_mfma_f32_16x16x32_bf16 v[62:65], v[134:137], v[184:187], v[62:65]
	v_mfma_f32_16x16x32_bf16 v[58:61], v[142:145], v[184:187], v[58:61]
	v_mfma_f32_16x16x32_bf16 v[46:49], v[134:137], v[192:195], v[46:49]
	v_mfma_f32_16x16x32_bf16 v[42:45], v[142:145], v[192:195], v[42:45]
	v_mfma_f32_16x16x32_bf16 v[30:33], v[134:137], v[200:203], v[30:33]
	v_mfma_f32_16x16x32_bf16 v[26:29], v[142:145], v[200:203], v[26:29]
	v_mfma_f32_16x16x32_bf16 v[14:17], v[134:137], v[208:211], v[14:17]
	v_mfma_f32_16x16x32_bf16 v[10:13], v[142:145], v[208:211], v[10:13]
	s_setprio 0
	s_setprio 1
	v_mfma_f32_16x16x32_bf16 v[54:57], v[146:149], v[172:175], v[54:57]
	v_mfma_f32_16x16x32_bf16 v[50:53], v[164:167], v[172:175], v[50:53]
	v_mfma_f32_16x16x32_bf16 v[38:41], v[146:149], v[188:191], v[38:41]
	v_mfma_f32_16x16x32_bf16 v[34:37], v[164:167], v[188:191], v[34:37]
	v_mfma_f32_16x16x32_bf16 v[22:25], v[146:149], v[196:199], v[22:25]
	v_mfma_f32_16x16x32_bf16 v[18:21], v[164:167], v[196:199], v[18:21]
	v_mfma_f32_16x16x32_bf16 v[6:9], v[146:149], v[204:207], v[6:9]
	v_mfma_f32_16x16x32_bf16 v[2:5], v[164:167], v[204:207], v[2:5]
	v_mfma_f32_16x16x32_bf16 v[54:57], v[150:153], v[184:187], v[54:57]
	v_mfma_f32_16x16x32_bf16 v[50:53], v[168:171], v[184:187], v[50:53]
	v_mfma_f32_16x16x32_bf16 v[38:41], v[150:153], v[192:195], v[38:41]
	v_mfma_f32_16x16x32_bf16 v[34:37], v[168:171], v[192:195], v[34:37]
	v_mfma_f32_16x16x32_bf16 v[22:25], v[150:153], v[200:203], v[22:25]
	v_mfma_f32_16x16x32_bf16 v[18:21], v[168:171], v[200:203], v[18:21]
	v_mfma_f32_16x16x32_bf16 v[6:9], v[150:153], v[208:211], v[6:9]
	v_mfma_f32_16x16x32_bf16 v[2:5], v[168:171], v[208:211], v[2:5]
	s_barrier
	s_setprio 0
	s_add_i32 s24, 0, 0x18000
	s_add_i32 s49, 0, 0x1c000
	v_add_u32_e32 v142, s24, v177
	v_add_u32_e32 v168, s49, v177
	ds_read_b128 v[130:133], v142
	ds_read_b128 v[134:137], v142 offset:1024
	ds_read_b128 v[138:141], v142 offset:2048
	ds_read_b128 v[142:145], v142 offset:3072
	ds_read_b128 v[146:149], v168
	ds_read_b128 v[150:153], v168 offset:1024
	ds_read_b128 v[164:167], v168 offset:2048
	ds_read_b128 v[168:171], v168 offset:3072
	s_add_u32 s22, s22, 0x200000
	s_addc_u32 s23, s23, 0
	s_mov_b32 m0, s62
	ds_read_b128 v[172:175], v181 offset:32768
	ds_read_b128 v[184:187], v181 offset:33792
	ds_read_b128 v[188:191], v181 offset:34816
	ds_read_b128 v[192:195], v181 offset:35840
	ds_read_b128 v[196:199], v181 offset:36864
	ds_read_b128 v[200:203], v181 offset:37888
	ds_read_b128 v[204:207], v181 offset:38912
	ds_read_b128 v[208:211], v181 offset:39936
	global_load_lds_dwordx4 v154, s[22:23]
	s_mov_b32 m0, s63
	s_nop 0
	global_load_lds_dwordx4 v156, s[22:23]
	s_waitcnt vmcnt(8)
	s_waitcnt lgkmcnt(0)
	s_setprio 1
	s_barrier
	v_mfma_f32_16x16x32_bf16 v[126:129], v[130:133], v[172:175], v[126:129]
	v_mfma_f32_16x16x32_bf16 v[122:125], v[138:141], v[172:175], v[122:125]
	v_mfma_f32_16x16x32_bf16 v[110:113], v[130:133], v[188:191], v[110:113]
	v_mfma_f32_16x16x32_bf16 v[106:109], v[138:141], v[188:191], v[106:109]
	v_mfma_f32_16x16x32_bf16 v[94:97], v[130:133], v[196:199], v[94:97]
	v_mfma_f32_16x16x32_bf16 v[90:93], v[138:141], v[196:199], v[90:93]
	v_mfma_f32_16x16x32_bf16 v[78:81], v[130:133], v[204:207], v[78:81]
	v_mfma_f32_16x16x32_bf16 v[74:77], v[138:141], v[204:207], v[74:77]
	v_mfma_f32_16x16x32_bf16 v[126:129], v[134:137], v[184:187], v[126:129]
	v_mfma_f32_16x16x32_bf16 v[122:125], v[142:145], v[184:187], v[122:125]
	v_mfma_f32_16x16x32_bf16 v[110:113], v[134:137], v[192:195], v[110:113]
	v_mfma_f32_16x16x32_bf16 v[106:109], v[142:145], v[192:195], v[106:109]
	v_mfma_f32_16x16x32_bf16 v[94:97], v[134:137], v[200:203], v[94:97]
	v_mfma_f32_16x16x32_bf16 v[90:93], v[142:145], v[200:203], v[90:93]
	v_mfma_f32_16x16x32_bf16 v[78:81], v[134:137], v[208:211], v[78:81]
	v_mfma_f32_16x16x32_bf16 v[74:77], v[142:145], v[208:211], v[74:77]
	s_setprio 0
	s_setprio 1
	v_mfma_f32_16x16x32_bf16 v[118:121], v[146:149], v[172:175], v[118:121]
	v_mfma_f32_16x16x32_bf16 v[114:117], v[164:167], v[172:175], v[114:117]
	v_mfma_f32_16x16x32_bf16 v[102:105], v[146:149], v[188:191], v[102:105]
	v_mfma_f32_16x16x32_bf16 v[98:101], v[164:167], v[188:191], v[98:101]
	v_mfma_f32_16x16x32_bf16 v[86:89], v[146:149], v[196:199], v[86:89]
	v_mfma_f32_16x16x32_bf16 v[82:85], v[164:167], v[196:199], v[82:85]
	v_mfma_f32_16x16x32_bf16 v[70:73], v[146:149], v[204:207], v[70:73]
	v_mfma_f32_16x16x32_bf16 v[66:69], v[164:167], v[204:207], v[66:69]
	v_mfma_f32_16x16x32_bf16 v[118:121], v[150:153], v[184:187], v[118:121]
	v_mfma_f32_16x16x32_bf16 v[114:117], v[168:171], v[184:187], v[114:117]
	v_mfma_f32_16x16x32_bf16 v[102:105], v[150:153], v[192:195], v[102:105]
	v_mfma_f32_16x16x32_bf16 v[98:101], v[168:171], v[192:195], v[98:101]
	v_mfma_f32_16x16x32_bf16 v[86:89], v[150:153], v[200:203], v[86:89]
	v_mfma_f32_16x16x32_bf16 v[82:85], v[168:171], v[200:203], v[82:85]
	v_mfma_f32_16x16x32_bf16 v[70:73], v[150:153], v[208:211], v[70:73]
	v_mfma_f32_16x16x32_bf16 v[66:69], v[168:171], v[208:211], v[66:69]
	s_barrier
	s_setprio 0
	s_add_i32 s22, s24, s57
	v_lshl_add_u64 v[212:213], v[212:213], 0, s[34:35]
	s_mov_b32 m0, s22
	ds_read_b128 v[172:175], v181 offset:49152
	ds_read_b128 v[184:187], v181 offset:50176
	ds_read_b128 v[188:191], v181 offset:51200
	ds_read_b128 v[192:195], v181 offset:52224
	ds_read_b128 v[196:199], v181 offset:53248
	ds_read_b128 v[200:203], v181 offset:54272
	ds_read_b128 v[204:207], v181 offset:55296
	ds_read_b128 v[208:211], v181 offset:56320
	global_load_lds_dwordx4 v[212:213], off
	s_add_i32 m0, s22, 0x2000
	s_add_u32 s22, s26, 0x200080
	v_lshl_add_u64 v[212:213], v[214:215], 0, s[34:35]
	s_addc_u32 s23, s27, 0
	s_add_i32 s24, s49, s57
	global_load_lds_dwordx4 v[212:213], off
	v_lshl_add_u64 v[212:213], s[22:23], 0, v[0:1]
	s_mov_b32 m0, s24
	s_nop 0
	global_load_lds_dwordx4 v[212:213], off
	s_add_i32 m0, s24, 0x2000
	s_nop 0
	global_load_lds_dwordx4 v158, s[22:23]
	v_lshl_add_u64 v[212:213], v[216:217], 0, s[34:35]
	s_mov_b32 m0, s74
	s_nop 0
	global_load_lds_dwordx4 v[212:213], off
	v_lshl_add_u64 v[212:213], v[218:219], 0, s[34:35]
	s_mov_b32 m0, s75
	s_nop 0
	global_load_lds_dwordx4 v[212:213], off
	s_waitcnt vmcnt(8)
	s_waitcnt lgkmcnt(0)
	s_setprio 1
	s_barrier
	v_mfma_f32_16x16x32_bf16 v[62:65], v[130:133], v[172:175], v[62:65]
	v_mfma_f32_16x16x32_bf16 v[58:61], v[138:141], v[172:175], v[58:61]
	v_mfma_f32_16x16x32_bf16 v[46:49], v[130:133], v[188:191], v[46:49]
	v_mfma_f32_16x16x32_bf16 v[42:45], v[138:141], v[188:191], v[42:45]
	v_mfma_f32_16x16x32_bf16 v[30:33], v[130:133], v[196:199], v[30:33]
	v_mfma_f32_16x16x32_bf16 v[26:29], v[138:141], v[196:199], v[26:29]
	v_mfma_f32_16x16x32_bf16 v[14:17], v[130:133], v[204:207], v[14:17]
	v_mfma_f32_16x16x32_bf16 v[10:13], v[138:141], v[204:207], v[10:13]
	v_mfma_f32_16x16x32_bf16 v[62:65], v[134:137], v[184:187], v[62:65]
	v_mfma_f32_16x16x32_bf16 v[58:61], v[142:145], v[184:187], v[58:61]
	v_mfma_f32_16x16x32_bf16 v[46:49], v[134:137], v[192:195], v[46:49]
	v_mfma_f32_16x16x32_bf16 v[42:45], v[142:145], v[192:195], v[42:45]
	v_mfma_f32_16x16x32_bf16 v[30:33], v[134:137], v[200:203], v[30:33]
	v_mfma_f32_16x16x32_bf16 v[26:29], v[142:145], v[200:203], v[26:29]
	v_mfma_f32_16x16x32_bf16 v[14:17], v[134:137], v[208:211], v[14:17]
	v_mfma_f32_16x16x32_bf16 v[10:13], v[142:145], v[208:211], v[10:13]
	s_setprio 0
	s_setprio 1
	v_mfma_f32_16x16x32_bf16 v[54:57], v[146:149], v[172:175], v[54:57]
	v_mfma_f32_16x16x32_bf16 v[50:53], v[164:167], v[172:175], v[50:53]
	v_mfma_f32_16x16x32_bf16 v[38:41], v[146:149], v[188:191], v[38:41]
	v_mfma_f32_16x16x32_bf16 v[34:37], v[164:167], v[188:191], v[34:37]
	v_mfma_f32_16x16x32_bf16 v[22:25], v[146:149], v[196:199], v[22:25]
	v_mfma_f32_16x16x32_bf16 v[18:21], v[164:167], v[196:199], v[18:21]
	v_mfma_f32_16x16x32_bf16 v[6:9], v[146:149], v[204:207], v[6:9]
	v_mfma_f32_16x16x32_bf16 v[2:5], v[164:167], v[204:207], v[2:5]
	v_mfma_f32_16x16x32_bf16 v[54:57], v[150:153], v[184:187], v[54:57]
	v_mfma_f32_16x16x32_bf16 v[50:53], v[168:171], v[184:187], v[50:53]
	v_mfma_f32_16x16x32_bf16 v[38:41], v[150:153], v[192:195], v[38:41]
	v_mfma_f32_16x16x32_bf16 v[34:37], v[168:171], v[192:195], v[34:37]
	v_mfma_f32_16x16x32_bf16 v[22:25], v[150:153], v[200:203], v[22:25]
	v_mfma_f32_16x16x32_bf16 v[18:21], v[168:171], v[200:203], v[18:21]
	v_mfma_f32_16x16x32_bf16 v[6:9], v[150:153], v[208:211], v[6:9]
	v_mfma_f32_16x16x32_bf16 v[2:5], v[168:171], v[208:211], v[2:5]
	s_barrier
	s_setprio 0
	s_add_i32 s48, s48, 2
	s_add_u32 s46, s46, 0x100
	s_addc_u32 s47, s47, 0
	s_add_u32 s36, s36, 0x100
	s_addc_u32 s37, s37, 0
	s_cmpk_gt_u32 s48, 0x7d
	s_cbranch_scc0 .LBB0_1004
	s_and_b64 vcc, exec, s[10:11]
	s_cbranch_vccz .LBB0_1007
	s_barrier
